# k=3 GEMM tiles: 3 of the 8 workgroup barriers per main-loop K-tile dropped (no instruction moved; vmcnt wait brought forward)
# speedup vs baseline: 1.0064x; 1.0027x over previous
.LBB0_251:
	v_and_b32_e32 v13, 15, v12
	v_or_b32_e32 v14, s59, v13
	v_and_b32_e32 v15, 48, v12
	v_lshlrev_b32_e32 v16, 6, v14
	s_movk_i32 s10, 0x3c0
	v_lshlrev_b32_e32 v12, 2, v12
	v_and_or_b32 v16, v16, s10, v15
	v_lshl_or_b32 v13, v13, 6, v15
	v_and_b32_e32 v12, 32, v12
	v_readlane_b32 s10, v254, 62
	v_readlane_b32 s27, v255, 1
	v_readlane_b32 s49, v255, 2
	v_bitop3_b32 v17, v13, s10, v12 bitop3:0xde
	s_add_u32 s10, s27, s2
	s_addc_u32 s11, s49, s3
	s_add_i32 s17, 0, 0x18000
	s_add_i32 vcc_hi, s17, s58
	v_lshl_add_u64 v[12:13], s[10:11], 0, v[4:5]
	s_mov_b32 m0, vcc_hi
	s_add_i32 vcc_lo, vcc_hi, 0x2000
	v_readlane_b32 s52, v255, 3
	s_waitcnt vmcnt(4)
	s_barrier
	global_load_lds_dwordx4 v[12:13], off
	v_lshl_add_u64 v[12:13], s[10:11], 0, v[6:7]
	s_add_u32 s10, s52, s54
	v_readlane_b32 s53, v255, 4
	s_mov_b32 m0, vcc_lo
	s_addc_u32 s11, s53, s55
	s_add_i32 s70, s69, 0x8000
	global_load_lds_dwordx4 v[12:13], off
	v_lshl_add_u64 v[12:13], s[10:11], 0, v[0:1]
	s_mov_b32 m0, s70
	s_add_i32 s68, s69, 0xa000
	global_load_lds_dwordx4 v[12:13], off
	v_lshl_add_u64 v[12:13], s[10:11], 0, v[2:3]
	s_add_u32 s10, s27, s56
	s_addc_u32 s11, s49, s57
	s_add_i32 s49, 0, 0x1c000
	s_mov_b32 m0, s68
	s_add_i32 s66, s49, s58
	global_load_lds_dwordx4 v[12:13], off
	v_lshl_add_u64 v[12:13], s[10:11], 0, v[4:5]
	s_mov_b32 m0, s66
	s_add_i32 s65, s66, 0x2000
	global_load_lds_dwordx4 v[12:13], off
	v_lshl_add_u64 v[12:13], s[10:11], 0, v[6:7]
	s_mov_b32 m0, s65
	v_lshlrev_b32_e32 v14, 2, v14
	global_load_lds_dwordx4 v[12:13], off
	v_and_b32_e32 v14, 32, v14
	s_add_i32 s91, 0, 0x10000
	v_bitop3_b32 v14, v16, s85, v14 bitop3:0xde
	v_add_u32_e32 v16, s91, v17
	s_waitcnt vmcnt(6)
	s_barrier
	ds_read_b128 v[18:21], v16
	ds_read_b128 v[22:25], v16 offset:1024
	ds_read_b128 v[26:29], v16 offset:2048
	ds_read_b128 v[30:33], v16 offset:3072
	s_add_i32 s50, 0, 0x14000
	v_add_u32_e32 v12, 0, v14
	v_add_u32_e32 v15, s50, v17
	v_add_u32_e32 v14, s17, v17
	v_add_u32_e32 v13, s49, v17
	s_add_u32 s10, s52, s40
	s_addc_u32 s11, s53, s41
	s_add_i32 s90, s69, 0xc000
	v_lshl_add_u64 v[62:63], s[10:11], 0, v[0:1]
	s_mov_b32 m0, s90
	s_add_i32 s53, s69, 0xe000
	ds_read_b128 v[34:37], v12
	ds_read_b128 v[38:41], v12 offset:1024
	ds_read_b128 v[42:45], v12 offset:2048
	ds_read_b128 v[46:49], v12 offset:3072
	ds_read_b128 v[50:53], v12 offset:4096
	ds_read_b128 v[54:57], v12 offset:5120
	ds_read_b128 v[58:61], v12 offset:6144
	ds_read_b128 v[66:69], v12 offset:7168
	global_load_lds_dwordx4 v[62:63], off
	v_lshl_add_u64 v[62:63], s[10:11], 0, v[2:3]
	s_mov_b32 m0, s53
	s_nop 0
	global_load_lds_dwordx4 v[62:63], off
	s_waitcnt lgkmcnt(8)
	s_barrier
	s_waitcnt lgkmcnt(0)
	s_setprio 1
	s_waitcnt lgkmcnt(0)
	v_mfma_f32_16x16x32_bf16 v[70:73], v[18:21], v[34:37], 0
	v_mfma_f32_16x16x32_bf16 v[74:77], v[26:29], v[34:37], 0
	v_mfma_f32_16x16x32_bf16 v[78:81], v[18:21], v[42:45], 0
	v_mfma_f32_16x16x32_bf16 v[82:85], v[26:29], v[42:45], 0
	v_mfma_f32_16x16x32_bf16 v[86:89], v[18:21], v[50:53], 0
	v_mfma_f32_16x16x32_bf16 v[90:93], v[26:29], v[50:53], 0
	v_mfma_f32_16x16x32_bf16 v[94:97], v[18:21], v[58:61], 0
	v_mfma_f32_16x16x32_bf16 v[98:101], v[26:29], v[58:61], 0
	v_mfma_f32_16x16x32_bf16 v[70:73], v[22:25], v[38:41], v[70:73]
	v_mfma_f32_16x16x32_bf16 v[74:77], v[30:33], v[38:41], v[74:77]
	v_mfma_f32_16x16x32_bf16 v[78:81], v[22:25], v[46:49], v[78:81]
	v_mfma_f32_16x16x32_bf16 v[82:85], v[30:33], v[46:49], v[82:85]
	v_mfma_f32_16x16x32_bf16 v[86:89], v[22:25], v[54:57], v[86:89]
	v_mfma_f32_16x16x32_bf16 v[90:93], v[30:33], v[54:57], v[90:93]
	v_mfma_f32_16x16x32_bf16 v[94:97], v[22:25], v[66:69], v[94:97]
	v_mfma_f32_16x16x32_bf16 v[98:101], v[30:33], v[66:69], v[98:101]
	s_setprio 0
	s_barrier
	v_readlane_b32 s17, v255, 5
	s_add_u32 s10, s17, s2
	v_readlane_b32 s27, v255, 6
	s_addc_u32 s11, s27, s3
	s_add_i32 s91, s91, s58
	v_lshl_add_u64 v[62:63], s[10:11], 0, v[4:5]
	s_mov_b32 m0, s91
	ds_read_b128 v[102:105], v15
	ds_read_b128 v[106:109], v15 offset:1024
	ds_read_b128 v[110:113], v15 offset:2048
	ds_read_b128 v[114:117], v15 offset:3072
	global_load_lds_dwordx4 v[62:63], off
	v_lshl_add_u64 v[62:63], s[10:11], 0, v[6:7]
	s_add_i32 s11, s91, 0x2000
	s_mov_b32 m0, s11
	s_nop 0
	global_load_lds_dwordx4 v[62:63], off
	s_waitcnt lgkmcnt(0)
	s_setprio 1
	s_waitcnt lgkmcnt(0)
	v_mfma_f32_16x16x32_bf16 v[118:121], v[102:105], v[34:37], 0
	v_mfma_f32_16x16x32_bf16 v[34:37], v[110:113], v[34:37], 0
	v_mfma_f32_16x16x32_bf16 v[118:121], v[106:109], v[38:41], v[118:121]
	v_mfma_f32_16x16x32_bf16 v[34:37], v[114:117], v[38:41], v[34:37]
	v_mfma_f32_16x16x32_bf16 v[38:41], v[102:105], v[42:45], 0
	v_mfma_f32_16x16x32_bf16 v[42:45], v[110:113], v[42:45], 0
	v_mfma_f32_16x16x32_bf16 v[38:41], v[106:109], v[46:49], v[38:41]
	v_mfma_f32_16x16x32_bf16 v[42:45], v[114:117], v[46:49], v[42:45]
	v_mfma_f32_16x16x32_bf16 v[46:49], v[102:105], v[50:53], 0
	v_mfma_f32_16x16x32_bf16 v[50:53], v[110:113], v[50:53], 0
	v_mfma_f32_16x16x32_bf16 v[46:49], v[106:109], v[54:57], v[46:49]
	v_mfma_f32_16x16x32_bf16 v[50:53], v[114:117], v[54:57], v[50:53]
	v_mfma_f32_16x16x32_bf16 v[54:57], v[102:105], v[58:61], 0
	v_mfma_f32_16x16x32_bf16 v[58:61], v[110:113], v[58:61], 0
	v_mfma_f32_16x16x32_bf16 v[54:57], v[106:109], v[66:69], v[54:57]
	v_mfma_f32_16x16x32_bf16 v[58:61], v[114:117], v[66:69], v[58:61]
	s_setprio 0
	v_readlane_b32 s52, v255, 7
	s_add_u32 s60, s52, s54
	v_readlane_b32 s86, v255, 8
	s_addc_u32 s61, s86, s55
	s_mov_b32 m0, s69
	v_lshl_add_u64 v[62:63], s[60:61], 0, v[0:1]
	s_barrier
	ds_read_b128 v[66:69], v12 offset:16384
	ds_read_b128 v[122:125], v12 offset:17408
	ds_read_b128 v[126:129], v12 offset:18432
	ds_read_b128 v[130:133], v12 offset:19456
	ds_read_b128 v[134:137], v12 offset:20480
	ds_read_b128 v[138:141], v12 offset:21504
	ds_read_b128 v[142:145], v12 offset:22528
	ds_read_b128 v[146:149], v12 offset:23552
	global_load_lds_dwordx4 v[62:63], off
	v_lshl_add_u64 v[62:63], s[60:61], 0, v[2:3]
	s_mov_b32 m0, s71
	s_nop 0
	global_load_lds_dwordx4 v[62:63], off
	s_waitcnt vmcnt(4)
	s_barrier
	s_waitcnt lgkmcnt(0)
	s_setprio 1
	s_waitcnt lgkmcnt(0)
	v_mfma_f32_16x16x32_bf16 v[150:153], v[18:21], v[66:69], 0
	v_mfma_f32_16x16x32_bf16 v[158:161], v[18:21], v[126:129], 0
	v_mfma_f32_16x16x32_bf16 v[166:169], v[18:21], v[134:137], 0
	v_mfma_f32_16x16x32_bf16 v[18:21], v[18:21], v[142:145], 0
	v_mfma_f32_16x16x32_bf16 v[150:153], v[22:25], v[122:125], v[150:153]
	v_mfma_f32_16x16x32_bf16 v[158:161], v[22:25], v[130:133], v[158:161]
	v_mfma_f32_16x16x32_bf16 v[166:169], v[22:25], v[138:141], v[166:169]
	v_mfma_f32_16x16x32_bf16 v[18:21], v[22:25], v[146:149], v[18:21]
	v_mfma_f32_16x16x32_bf16 v[22:25], v[26:29], v[142:145], 0
	v_mfma_f32_16x16x32_bf16 v[154:157], v[26:29], v[66:69], 0
	v_mfma_f32_16x16x32_bf16 v[162:165], v[26:29], v[126:129], 0
	v_mfma_f32_16x16x32_bf16 v[170:173], v[26:29], v[134:137], 0
	v_mfma_f32_16x16x32_bf16 v[22:25], v[30:33], v[146:149], v[22:25]
	v_mfma_f32_16x16x32_bf16 v[154:157], v[30:33], v[122:125], v[154:157]
	v_mfma_f32_16x16x32_bf16 v[162:165], v[30:33], v[130:133], v[162:165]
	v_mfma_f32_16x16x32_bf16 v[170:173], v[30:33], v[138:141], v[170:173]
	s_setprio 0
	s_add_u32 s60, s17, s56
	s_addc_u32 s61, s27, s57
	s_add_i32 s49, s50, s58
	v_lshl_add_u64 v[26:27], s[60:61], 0, v[4:5]
	s_mov_b32 m0, s49
	s_add_i32 s10, s49, 0x2000
	global_load_lds_dwordx4 v[26:27], off
	v_lshl_add_u64 v[26:27], s[60:61], 0, v[6:7]
	s_mov_b32 m0, s10
	s_nop 0
	global_load_lds_dwordx4 v[26:27], off
	s_waitcnt vmcnt(6)
	s_setprio 1
	v_mfma_f32_16x16x32_bf16 v[26:29], v[102:105], v[66:69], 0
	v_mfma_f32_16x16x32_bf16 v[30:33], v[110:113], v[66:69], 0
	v_mfma_f32_16x16x32_bf16 v[26:29], v[106:109], v[122:125], v[26:29]
	v_mfma_f32_16x16x32_bf16 v[30:33], v[114:117], v[122:125], v[30:33]
	v_mfma_f32_16x16x32_bf16 v[66:69], v[102:105], v[126:129], 0
	v_mfma_f32_16x16x32_bf16 v[122:125], v[110:113], v[126:129], 0
	v_mfma_f32_16x16x32_bf16 v[126:129], v[102:105], v[134:137], 0
	v_mfma_f32_16x16x32_bf16 v[102:105], v[102:105], v[142:145], 0
	v_mfma_f32_16x16x32_bf16 v[66:69], v[106:109], v[130:133], v[66:69]
	v_mfma_f32_16x16x32_bf16 v[126:129], v[106:109], v[138:141], v[126:129]
	v_mfma_f32_16x16x32_bf16 v[102:105], v[106:109], v[146:149], v[102:105]
	v_mfma_f32_16x16x32_bf16 v[106:109], v[110:113], v[142:145], 0
	v_mfma_f32_16x16x32_bf16 v[122:125], v[114:117], v[130:133], v[122:125]
	v_mfma_f32_16x16x32_bf16 v[130:133], v[110:113], v[134:137], 0
	v_mfma_f32_16x16x32_bf16 v[106:109], v[114:117], v[146:149], v[106:109]
	v_mfma_f32_16x16x32_bf16 v[130:133], v[114:117], v[138:141], v[130:133]
	s_setprio 0
	s_barrier
	ds_read_b128 v[110:113], v14
	ds_read_b128 v[114:117], v14 offset:1024
	ds_read_b128 v[134:137], v14 offset:2048
	ds_read_b128 v[138:141], v14 offset:3072
	s_add_u32 s60, s52, s40
	s_addc_u32 s61, s86, s41
	s_mov_b32 m0, s67
	v_lshl_add_u64 v[62:63], s[60:61], 0, v[0:1]
	ds_read_b128 v[142:145], v12 offset:32768
	ds_read_b128 v[146:149], v12 offset:33792
	ds_read_b128 v[174:177], v12 offset:34816
	ds_read_b128 v[178:181], v12 offset:35840
	ds_read_b128 v[182:185], v12 offset:36864
	ds_read_b128 v[190:193], v12 offset:37888
	ds_read_b128 v[194:197], v12 offset:38912
	ds_read_b128 v[198:201], v12 offset:39936
	global_load_lds_dwordx4 v[62:63], off
	v_lshl_add_u64 v[62:63], s[60:61], 0, v[2:3]
	s_mov_b32 m0, s64
	s_nop 0
	global_load_lds_dwordx4 v[62:63], off
	s_waitcnt lgkmcnt(8)
	s_barrier
	s_waitcnt lgkmcnt(0)
	s_setprio 1
	s_waitcnt lgkmcnt(0)
	v_mfma_f32_16x16x32_bf16 v[70:73], v[110:113], v[142:145], v[70:73]
	v_mfma_f32_16x16x32_bf16 v[74:77], v[134:137], v[142:145], v[74:77]
	v_mfma_f32_16x16x32_bf16 v[78:81], v[110:113], v[174:177], v[78:81]
	v_mfma_f32_16x16x32_bf16 v[82:85], v[134:137], v[174:177], v[82:85]
	v_mfma_f32_16x16x32_bf16 v[86:89], v[110:113], v[182:185], v[86:89]
	v_mfma_f32_16x16x32_bf16 v[90:93], v[134:137], v[182:185], v[90:93]
	v_mfma_f32_16x16x32_bf16 v[94:97], v[110:113], v[194:197], v[94:97]
	v_mfma_f32_16x16x32_bf16 v[98:101], v[134:137], v[194:197], v[98:101]
	v_mfma_f32_16x16x32_bf16 v[70:73], v[114:117], v[146:149], v[70:73]
	v_mfma_f32_16x16x32_bf16 v[74:77], v[138:141], v[146:149], v[74:77]
	v_mfma_f32_16x16x32_bf16 v[78:81], v[114:117], v[178:181], v[78:81]
	v_mfma_f32_16x16x32_bf16 v[82:85], v[138:141], v[178:181], v[82:85]
	v_mfma_f32_16x16x32_bf16 v[86:89], v[114:117], v[190:193], v[86:89]
	v_mfma_f32_16x16x32_bf16 v[90:93], v[138:141], v[190:193], v[90:93]
	v_mfma_f32_16x16x32_bf16 v[94:97], v[114:117], v[198:201], v[94:97]
	v_mfma_f32_16x16x32_bf16 v[98:101], v[138:141], v[198:201], v[98:101]
	s_setprio 0
	s_barrier
	v_readlane_b32 s27, v255, 9
	s_add_u32 s60, s27, s2
	v_readlane_b32 s17, v255, 10
	s_addc_u32 s61, s17, s3
	s_mov_b32 m0, vcc_hi
	v_lshl_add_u64 v[62:63], s[60:61], 0, v[4:5]
	ds_read_b128 v[214:217], v13
	ds_read_b128 v[218:221], v13 offset:1024
	ds_read_b128 v[222:225], v13 offset:2048
	ds_read_b128 v[226:229], v13 offset:3072
	global_load_lds_dwordx4 v[62:63], off
	v_lshl_add_u64 v[62:63], s[60:61], 0, v[6:7]
	s_mov_b32 m0, vcc_lo
	s_nop 0
	global_load_lds_dwordx4 v[62:63], off
	s_waitcnt lgkmcnt(0)
	s_setprio 1
	s_waitcnt lgkmcnt(0)
	v_mfma_f32_16x16x32_bf16 v[118:121], v[214:217], v[142:145], v[118:121]
	v_mfma_f32_16x16x32_bf16 v[34:37], v[222:225], v[142:145], v[34:37]
	v_mfma_f32_16x16x32_bf16 v[38:41], v[214:217], v[174:177], v[38:41]
	v_mfma_f32_16x16x32_bf16 v[42:45], v[222:225], v[174:177], v[42:45]
	v_mfma_f32_16x16x32_bf16 v[46:49], v[214:217], v[182:185], v[46:49]
	v_mfma_f32_16x16x32_bf16 v[50:53], v[222:225], v[182:185], v[50:53]
	v_mfma_f32_16x16x32_bf16 v[54:57], v[214:217], v[194:197], v[54:57]
	v_mfma_f32_16x16x32_bf16 v[58:61], v[222:225], v[194:197], v[58:61]
	v_mfma_f32_16x16x32_bf16 v[118:121], v[218:221], v[146:149], v[118:121]
	v_mfma_f32_16x16x32_bf16 v[34:37], v[226:229], v[146:149], v[34:37]
	v_mfma_f32_16x16x32_bf16 v[38:41], v[218:221], v[178:181], v[38:41]
	v_mfma_f32_16x16x32_bf16 v[42:45], v[226:229], v[178:181], v[42:45]
	v_mfma_f32_16x16x32_bf16 v[46:49], v[218:221], v[190:193], v[46:49]
	v_mfma_f32_16x16x32_bf16 v[50:53], v[226:229], v[190:193], v[50:53]
	v_mfma_f32_16x16x32_bf16 v[54:57], v[218:221], v[198:201], v[54:57]
	v_mfma_f32_16x16x32_bf16 v[58:61], v[226:229], v[198:201], v[58:61]
	s_setprio 0
	s_mov_b64 s[60:61], 0x180
	s_mov_b32 m0, s70
	v_lshl_add_u64 v[62:63], v[8:9], 0, s[60:61]
	s_barrier
	ds_read_b128 v[142:145], v12 offset:49152
	ds_read_b128 v[146:149], v12 offset:50176
	ds_read_b128 v[174:177], v12 offset:51200
	ds_read_b128 v[178:181], v12 offset:52224
	ds_read_b128 v[182:185], v12 offset:53248
	ds_read_b128 v[190:193], v12 offset:54272
	ds_read_b128 v[194:197], v12 offset:55296
	ds_read_b128 v[198:201], v12 offset:56320
	global_load_lds_dwordx4 v[62:63], off
	v_lshl_add_u64 v[62:63], v[10:11], 0, s[60:61]
	s_mov_b32 m0, s68
	s_nop 0
	global_load_lds_dwordx4 v[62:63], off
	s_waitcnt vmcnt(4)
	s_barrier
	s_waitcnt lgkmcnt(0)
	s_setprio 1
	s_waitcnt lgkmcnt(0)
	v_mfma_f32_16x16x32_bf16 v[18:21], v[110:113], v[194:197], v[18:21]
	v_mfma_f32_16x16x32_bf16 v[22:25], v[134:137], v[194:197], v[22:25]
	v_mfma_f32_16x16x32_bf16 v[150:153], v[110:113], v[142:145], v[150:153]
	v_mfma_f32_16x16x32_bf16 v[154:157], v[134:137], v[142:145], v[154:157]
	v_mfma_f32_16x16x32_bf16 v[158:161], v[110:113], v[174:177], v[158:161]
	v_mfma_f32_16x16x32_bf16 v[162:165], v[134:137], v[174:177], v[162:165]
	v_mfma_f32_16x16x32_bf16 v[166:169], v[110:113], v[182:185], v[166:169]
	v_mfma_f32_16x16x32_bf16 v[170:173], v[134:137], v[182:185], v[170:173]
	v_mfma_f32_16x16x32_bf16 v[18:21], v[114:117], v[198:201], v[18:21]
	v_mfma_f32_16x16x32_bf16 v[22:25], v[138:141], v[198:201], v[22:25]
	v_mfma_f32_16x16x32_bf16 v[150:153], v[114:117], v[146:149], v[150:153]
	v_mfma_f32_16x16x32_bf16 v[154:157], v[138:141], v[146:149], v[154:157]
	v_mfma_f32_16x16x32_bf16 v[158:161], v[114:117], v[178:181], v[158:161]
	v_mfma_f32_16x16x32_bf16 v[162:165], v[138:141], v[178:181], v[162:165]
	v_mfma_f32_16x16x32_bf16 v[166:169], v[114:117], v[190:193], v[166:169]
	v_mfma_f32_16x16x32_bf16 v[170:173], v[138:141], v[190:193], v[170:173]
	s_setprio 0
	s_add_u32 s60, s27, s56
	s_addc_u32 s61, s17, s57
	s_mov_b32 m0, s66
	v_lshl_add_u64 v[62:63], s[60:61], 0, v[4:5]
	global_load_lds_dwordx4 v[62:63], off
	v_lshl_add_u64 v[62:63], s[60:61], 0, v[6:7]
	s_mov_b32 m0, s65
	s_nop 0
	global_load_lds_dwordx4 v[62:63], off
	s_waitcnt vmcnt(6)
	s_setprio 1
	v_mfma_f32_16x16x32_bf16 v[26:29], v[214:217], v[142:145], v[26:29]
	v_mfma_f32_16x16x32_bf16 v[30:33], v[222:225], v[142:145], v[30:33]
	v_mfma_f32_16x16x32_bf16 v[66:69], v[214:217], v[174:177], v[66:69]
	v_mfma_f32_16x16x32_bf16 v[110:113], v[222:225], v[174:177], v[122:125]
	v_mfma_f32_16x16x32_bf16 v[114:117], v[214:217], v[182:185], v[126:129]
	v_mfma_f32_16x16x32_bf16 v[122:125], v[222:225], v[182:185], v[130:133]
	v_mfma_f32_16x16x32_bf16 v[102:105], v[214:217], v[194:197], v[102:105]
	v_mfma_f32_16x16x32_bf16 v[106:109], v[222:225], v[194:197], v[106:109]
	v_mfma_f32_16x16x32_bf16 v[26:29], v[218:221], v[146:149], v[26:29]
	v_mfma_f32_16x16x32_bf16 v[30:33], v[226:229], v[146:149], v[30:33]
	v_mfma_f32_16x16x32_bf16 v[66:69], v[218:221], v[178:181], v[66:69]
	v_mfma_f32_16x16x32_bf16 v[110:113], v[226:229], v[178:181], v[110:113]
	v_mfma_f32_16x16x32_bf16 v[114:117], v[218:221], v[190:193], v[114:117]
	v_mfma_f32_16x16x32_bf16 v[122:125], v[226:229], v[190:193], v[122:125]
	v_mfma_f32_16x16x32_bf16 v[102:105], v[218:221], v[198:201], v[102:105]
	v_mfma_f32_16x16x32_bf16 v[106:109], v[226:229], v[198:201], v[106:109]
	s_setprio 0
	s_barrier
	ds_read_b128 v[126:129], v16
	ds_read_b128 v[130:133], v16 offset:1024
	ds_read_b128 v[134:137], v16 offset:2048
	ds_read_b128 v[138:141], v16 offset:3072
	v_readlane_b32 s17, v255, 11
	s_add_u32 s60, s17, s40
	v_readlane_b32 s17, v255, 12
	s_addc_u32 s61, s17, s41
	s_mov_b32 m0, s90
	v_lshl_add_u64 v[62:63], s[60:61], 0, v[0:1]
	ds_read_b128 v[142:145], v12
	ds_read_b128 v[146:149], v12 offset:1024
	ds_read_b128 v[174:177], v12 offset:2048
	ds_read_b128 v[178:181], v12 offset:3072
	ds_read_b128 v[182:185], v12 offset:4096
	ds_read_b128 v[190:193], v12 offset:5120
	ds_read_b128 v[194:197], v12 offset:6144
	ds_read_b128 v[198:201], v12 offset:7168
	global_load_lds_dwordx4 v[62:63], off
	v_lshl_add_u64 v[62:63], s[60:61], 0, v[2:3]
	s_mov_b32 m0, s53
	s_nop 0
	global_load_lds_dwordx4 v[62:63], off
	s_waitcnt lgkmcnt(8)
	s_barrier
	s_waitcnt lgkmcnt(0)
	s_setprio 1
	s_waitcnt lgkmcnt(0)
	v_mfma_f32_16x16x32_bf16 v[70:73], v[126:129], v[142:145], v[70:73]
	v_mfma_f32_16x16x32_bf16 v[74:77], v[134:137], v[142:145], v[74:77]
	v_mfma_f32_16x16x32_bf16 v[78:81], v[126:129], v[174:177], v[78:81]
	v_mfma_f32_16x16x32_bf16 v[82:85], v[134:137], v[174:177], v[82:85]
	v_mfma_f32_16x16x32_bf16 v[86:89], v[126:129], v[182:185], v[86:89]
	v_mfma_f32_16x16x32_bf16 v[90:93], v[134:137], v[182:185], v[90:93]
	v_mfma_f32_16x16x32_bf16 v[94:97], v[126:129], v[194:197], v[94:97]
	v_mfma_f32_16x16x32_bf16 v[98:101], v[134:137], v[194:197], v[98:101]
	v_mfma_f32_16x16x32_bf16 v[70:73], v[130:133], v[146:149], v[70:73]
	v_mfma_f32_16x16x32_bf16 v[74:77], v[138:141], v[146:149], v[74:77]
	v_mfma_f32_16x16x32_bf16 v[78:81], v[130:133], v[178:181], v[78:81]
	v_mfma_f32_16x16x32_bf16 v[82:85], v[138:141], v[178:181], v[82:85]
	v_mfma_f32_16x16x32_bf16 v[86:89], v[130:133], v[190:193], v[86:89]
	v_mfma_f32_16x16x32_bf16 v[90:93], v[138:141], v[190:193], v[90:93]
	v_mfma_f32_16x16x32_bf16 v[94:97], v[130:133], v[198:201], v[94:97]
	v_mfma_f32_16x16x32_bf16 v[98:101], v[138:141], v[198:201], v[98:101]
	s_setprio 0
	s_barrier
	v_readlane_b32 s17, v255, 13
	s_add_u32 s60, s17, s2
	v_readlane_b32 s27, v255, 14
	s_addc_u32 s61, s27, s3
	s_mov_b32 m0, s91
	v_lshl_add_u64 v[62:63], s[60:61], 0, v[4:5]
	ds_read_b128 v[214:217], v15
	ds_read_b128 v[218:221], v15 offset:1024
	ds_read_b128 v[222:225], v15 offset:2048
	ds_read_b128 v[226:229], v15 offset:3072
	global_load_lds_dwordx4 v[62:63], off
	v_lshl_add_u64 v[62:63], s[60:61], 0, v[6:7]
	s_mov_b32 m0, s11
	s_nop 0
	global_load_lds_dwordx4 v[62:63], off
	s_waitcnt lgkmcnt(0)
	s_setprio 1
	s_waitcnt lgkmcnt(0)
	v_mfma_f32_16x16x32_bf16 v[118:121], v[214:217], v[142:145], v[118:121]
	v_mfma_f32_16x16x32_bf16 v[34:37], v[222:225], v[142:145], v[34:37]
	v_mfma_f32_16x16x32_bf16 v[38:41], v[214:217], v[174:177], v[38:41]
	v_mfma_f32_16x16x32_bf16 v[42:45], v[222:225], v[174:177], v[42:45]
	v_mfma_f32_16x16x32_bf16 v[46:49], v[214:217], v[182:185], v[46:49]
	v_mfma_f32_16x16x32_bf16 v[50:53], v[222:225], v[182:185], v[50:53]
	v_mfma_f32_16x16x32_bf16 v[54:57], v[214:217], v[194:197], v[54:57]
	v_mfma_f32_16x16x32_bf16 v[58:61], v[222:225], v[194:197], v[58:61]
	v_mfma_f32_16x16x32_bf16 v[118:121], v[218:221], v[146:149], v[118:121]
	v_mfma_f32_16x16x32_bf16 v[34:37], v[226:229], v[146:149], v[34:37]
	v_mfma_f32_16x16x32_bf16 v[38:41], v[218:221], v[178:181], v[38:41]
	v_mfma_f32_16x16x32_bf16 v[42:45], v[226:229], v[178:181], v[42:45]
	v_mfma_f32_16x16x32_bf16 v[46:49], v[218:221], v[190:193], v[46:49]
	v_mfma_f32_16x16x32_bf16 v[50:53], v[226:229], v[190:193], v[50:53]
	v_mfma_f32_16x16x32_bf16 v[54:57], v[218:221], v[198:201], v[54:57]
	v_mfma_f32_16x16x32_bf16 v[58:61], v[226:229], v[198:201], v[58:61]
	s_setprio 0
	v_readlane_b32 s11, v255, 15
	s_add_u32 s54, s11, s54
	v_readlane_b32 s50, v255, 16
	s_addc_u32 s55, s50, s55
	s_mov_b32 m0, s69
	v_lshl_add_u64 v[62:63], s[54:55], 0, v[0:1]
	s_barrier
	ds_read_b128 v[142:145], v12 offset:16384
	ds_read_b128 v[146:149], v12 offset:17408
	ds_read_b128 v[174:177], v12 offset:18432
	ds_read_b128 v[178:181], v12 offset:19456
	ds_read_b128 v[182:185], v12 offset:20480
	ds_read_b128 v[190:193], v12 offset:21504
	ds_read_b128 v[194:197], v12 offset:22528
	ds_read_b128 v[198:201], v12 offset:23552
	global_load_lds_dwordx4 v[62:63], off
	v_lshl_add_u64 v[62:63], s[54:55], 0, v[2:3]
	s_mov_b32 m0, s71
	s_nop 0
	global_load_lds_dwordx4 v[62:63], off
	s_waitcnt vmcnt(4)
	s_barrier
	s_waitcnt lgkmcnt(0)
	s_setprio 1
	s_waitcnt lgkmcnt(0)
	v_mfma_f32_16x16x32_bf16 v[18:21], v[126:129], v[194:197], v[18:21]
	v_mfma_f32_16x16x32_bf16 v[22:25], v[134:137], v[194:197], v[22:25]
	v_mfma_f32_16x16x32_bf16 v[150:153], v[126:129], v[142:145], v[150:153]
	v_mfma_f32_16x16x32_bf16 v[154:157], v[134:137], v[142:145], v[154:157]
	v_mfma_f32_16x16x32_bf16 v[158:161], v[126:129], v[174:177], v[158:161]
	v_mfma_f32_16x16x32_bf16 v[162:165], v[134:137], v[174:177], v[162:165]
	v_mfma_f32_16x16x32_bf16 v[166:169], v[126:129], v[182:185], v[166:169]
	v_mfma_f32_16x16x32_bf16 v[170:173], v[134:137], v[182:185], v[170:173]
	v_mfma_f32_16x16x32_bf16 v[18:21], v[130:133], v[198:201], v[18:21]
	v_mfma_f32_16x16x32_bf16 v[22:25], v[138:141], v[198:201], v[22:25]
	v_mfma_f32_16x16x32_bf16 v[150:153], v[130:133], v[146:149], v[150:153]
	v_mfma_f32_16x16x32_bf16 v[154:157], v[138:141], v[146:149], v[154:157]
	v_mfma_f32_16x16x32_bf16 v[158:161], v[130:133], v[178:181], v[158:161]
	v_mfma_f32_16x16x32_bf16 v[162:165], v[138:141], v[178:181], v[162:165]
	v_mfma_f32_16x16x32_bf16 v[166:169], v[130:133], v[190:193], v[166:169]
	v_mfma_f32_16x16x32_bf16 v[170:173], v[138:141], v[190:193], v[170:173]
	s_setprio 0
	s_add_u32 s54, s17, s56
	s_addc_u32 s55, s27, s57
	s_mov_b32 m0, s49
	v_lshl_add_u64 v[62:63], s[54:55], 0, v[4:5]
	global_load_lds_dwordx4 v[62:63], off
	v_lshl_add_u64 v[62:63], s[54:55], 0, v[6:7]
	s_mov_b32 m0, s10
	s_nop 0
	global_load_lds_dwordx4 v[62:63], off
	s_waitcnt vmcnt(6)
	s_setprio 1
	v_mfma_f32_16x16x32_bf16 v[26:29], v[214:217], v[142:145], v[26:29]
	v_mfma_f32_16x16x32_bf16 v[30:33], v[222:225], v[142:145], v[30:33]
	v_mfma_f32_16x16x32_bf16 v[66:69], v[214:217], v[174:177], v[66:69]
	v_mfma_f32_16x16x32_bf16 v[110:113], v[222:225], v[174:177], v[110:113]
	v_mfma_f32_16x16x32_bf16 v[114:117], v[214:217], v[182:185], v[114:117]
	v_mfma_f32_16x16x32_bf16 v[122:125], v[222:225], v[182:185], v[122:125]
	v_mfma_f32_16x16x32_bf16 v[102:105], v[214:217], v[194:197], v[102:105]
	v_mfma_f32_16x16x32_bf16 v[106:109], v[222:225], v[194:197], v[106:109]
	v_mfma_f32_16x16x32_bf16 v[26:29], v[218:221], v[146:149], v[26:29]
	v_mfma_f32_16x16x32_bf16 v[30:33], v[226:229], v[146:149], v[30:33]
	v_mfma_f32_16x16x32_bf16 v[66:69], v[218:221], v[178:181], v[66:69]
	v_mfma_f32_16x16x32_bf16 v[110:113], v[226:229], v[178:181], v[110:113]
	v_mfma_f32_16x16x32_bf16 v[114:117], v[218:221], v[190:193], v[114:117]
	v_mfma_f32_16x16x32_bf16 v[122:125], v[226:229], v[190:193], v[122:125]
	v_mfma_f32_16x16x32_bf16 v[102:105], v[218:221], v[198:201], v[102:105]
	v_mfma_f32_16x16x32_bf16 v[106:109], v[226:229], v[198:201], v[106:109]
	s_setprio 0
	s_barrier
	ds_read_b128 v[126:129], v14
	ds_read_b128 v[130:133], v14 offset:1024
	ds_read_b128 v[134:137], v14 offset:2048
	ds_read_b128 v[138:141], v14 offset:3072
	s_add_u32 s10, s11, s40
	s_addc_u32 s11, s50, s41
	s_mov_b32 m0, s67
	v_lshl_add_u64 v[62:63], s[10:11], 0, v[0:1]
	ds_read_b128 v[142:145], v12 offset:32768
	ds_read_b128 v[146:149], v12 offset:33792
	ds_read_b128 v[174:177], v12 offset:34816
	ds_read_b128 v[178:181], v12 offset:35840
	ds_read_b128 v[182:185], v12 offset:36864
	ds_read_b128 v[190:193], v12 offset:37888
	ds_read_b128 v[194:197], v12 offset:38912
	ds_read_b128 v[198:201], v12 offset:39936
	global_load_lds_dwordx4 v[62:63], off
	v_lshl_add_u64 v[62:63], s[10:11], 0, v[2:3]
	s_mov_b32 m0, s64
	s_nop 0
	global_load_lds_dwordx4 v[62:63], off
	s_waitcnt lgkmcnt(8)
	s_barrier
	s_waitcnt lgkmcnt(0)
	s_setprio 1
	s_waitcnt lgkmcnt(0)
	v_mfma_f32_16x16x32_bf16 v[70:73], v[126:129], v[142:145], v[70:73]
	v_mfma_f32_16x16x32_bf16 v[74:77], v[134:137], v[142:145], v[74:77]
	v_mfma_f32_16x16x32_bf16 v[78:81], v[126:129], v[174:177], v[78:81]
	v_mfma_f32_16x16x32_bf16 v[82:85], v[134:137], v[174:177], v[82:85]
	v_mfma_f32_16x16x32_bf16 v[86:89], v[126:129], v[182:185], v[86:89]
	v_mfma_f32_16x16x32_bf16 v[90:93], v[134:137], v[182:185], v[90:93]
	v_mfma_f32_16x16x32_bf16 v[94:97], v[126:129], v[194:197], v[94:97]
	v_mfma_f32_16x16x32_bf16 v[98:101], v[134:137], v[194:197], v[98:101]
	v_mfma_f32_16x16x32_bf16 v[70:73], v[130:133], v[146:149], v[70:73]
	v_mfma_f32_16x16x32_bf16 v[74:77], v[138:141], v[146:149], v[74:77]
	v_mfma_f32_16x16x32_bf16 v[78:81], v[130:133], v[178:181], v[78:81]
	v_mfma_f32_16x16x32_bf16 v[82:85], v[138:141], v[178:181], v[82:85]
	v_mfma_f32_16x16x32_bf16 v[86:89], v[130:133], v[190:193], v[86:89]
	v_mfma_f32_16x16x32_bf16 v[90:93], v[138:141], v[190:193], v[90:93]
	v_mfma_f32_16x16x32_bf16 v[94:97], v[130:133], v[198:201], v[94:97]
	v_mfma_f32_16x16x32_bf16 v[98:101], v[138:141], v[198:201], v[98:101]
	s_setprio 0
	s_barrier
	v_readlane_b32 s10, v255, 17
	s_add_u32 s2, s10, s2
	v_readlane_b32 s11, v255, 18
	s_addc_u32 s3, s11, s3
	s_mov_b32 m0, vcc_hi
	v_lshl_add_u64 v[62:63], s[2:3], 0, v[4:5]
	ds_read_b128 v[214:217], v13
	ds_read_b128 v[218:221], v13 offset:1024
	ds_read_b128 v[222:225], v13 offset:2048
	ds_read_b128 v[226:229], v13 offset:3072
	global_load_lds_dwordx4 v[62:63], off
	v_lshl_add_u64 v[62:63], s[2:3], 0, v[6:7]
	s_mov_b32 m0, vcc_lo
	s_nop 0
	global_load_lds_dwordx4 v[62:63], off
	s_waitcnt lgkmcnt(0)
	s_setprio 1
	s_waitcnt lgkmcnt(0)
	v_mfma_f32_16x16x32_bf16 v[118:121], v[214:217], v[142:145], v[118:121]
	v_mfma_f32_16x16x32_bf16 v[34:37], v[222:225], v[142:145], v[34:37]
	v_mfma_f32_16x16x32_bf16 v[38:41], v[214:217], v[174:177], v[38:41]
	v_mfma_f32_16x16x32_bf16 v[42:45], v[222:225], v[174:177], v[42:45]
	v_mfma_f32_16x16x32_bf16 v[46:49], v[214:217], v[182:185], v[46:49]
	v_mfma_f32_16x16x32_bf16 v[50:53], v[222:225], v[182:185], v[50:53]
	v_mfma_f32_16x16x32_bf16 v[54:57], v[214:217], v[194:197], v[54:57]
	v_mfma_f32_16x16x32_bf16 v[58:61], v[222:225], v[194:197], v[58:61]
	v_mfma_f32_16x16x32_bf16 v[118:121], v[218:221], v[146:149], v[118:121]
	v_mfma_f32_16x16x32_bf16 v[34:37], v[226:229], v[146:149], v[34:37]
	v_mfma_f32_16x16x32_bf16 v[38:41], v[218:221], v[178:181], v[38:41]
	v_mfma_f32_16x16x32_bf16 v[42:45], v[226:229], v[178:181], v[42:45]
	v_mfma_f32_16x16x32_bf16 v[46:49], v[218:221], v[190:193], v[46:49]
	v_mfma_f32_16x16x32_bf16 v[50:53], v[226:229], v[190:193], v[50:53]
	v_mfma_f32_16x16x32_bf16 v[54:57], v[218:221], v[198:201], v[54:57]
	v_mfma_f32_16x16x32_bf16 v[58:61], v[226:229], v[198:201], v[58:61]
	s_setprio 0
	s_mov_b64 s[2:3], 0x280
	s_mov_b32 m0, s70
	v_lshl_add_u64 v[8:9], v[8:9], 0, s[2:3]
	s_barrier
	ds_read_b128 v[142:145], v12 offset:49152
	ds_read_b128 v[146:149], v12 offset:50176
	ds_read_b128 v[174:177], v12 offset:51200
	ds_read_b128 v[178:181], v12 offset:52224
	ds_read_b128 v[182:185], v12 offset:53248
	ds_read_b128 v[190:193], v12 offset:54272
	ds_read_b128 v[194:197], v12 offset:55296
	ds_read_b128 v[198:201], v12 offset:56320
	global_load_lds_dwordx4 v[8:9], off
	v_lshl_add_u64 v[8:9], v[10:11], 0, s[2:3]
	s_mov_b32 m0, s68
	s_nop 0
	global_load_lds_dwordx4 v[8:9], off
	s_waitcnt vmcnt(4)
	s_barrier
	s_waitcnt lgkmcnt(0)
	s_setprio 1
	s_waitcnt lgkmcnt(0)
	v_mfma_f32_16x16x32_bf16 v[8:11], v[126:129], v[142:145], v[150:153]
	v_mfma_f32_16x16x32_bf16 v[18:21], v[126:129], v[194:197], v[18:21]
	v_mfma_f32_16x16x32_bf16 v[22:25], v[134:137], v[194:197], v[22:25]
	v_mfma_f32_16x16x32_bf16 v[8:11], v[130:133], v[146:149], v[8:11]
	v_mfma_f32_16x16x32_bf16 v[150:153], v[134:137], v[142:145], v[154:157]
	v_mfma_f32_16x16x32_bf16 v[154:157], v[126:129], v[174:177], v[158:161]
	v_mfma_f32_16x16x32_bf16 v[158:161], v[134:137], v[174:177], v[162:165]
	v_mfma_f32_16x16x32_bf16 v[162:165], v[126:129], v[182:185], v[166:169]
	v_mfma_f32_16x16x32_bf16 v[166:169], v[134:137], v[182:185], v[170:173]
	v_mfma_f32_16x16x32_bf16 v[18:21], v[130:133], v[198:201], v[18:21]
	v_mfma_f32_16x16x32_bf16 v[22:25], v[138:141], v[198:201], v[22:25]
	v_mfma_f32_16x16x32_bf16 v[150:153], v[138:141], v[146:149], v[150:153]
	v_mfma_f32_16x16x32_bf16 v[154:157], v[130:133], v[178:181], v[154:157]
	v_mfma_f32_16x16x32_bf16 v[158:161], v[138:141], v[178:181], v[158:161]
	v_mfma_f32_16x16x32_bf16 v[162:165], v[130:133], v[190:193], v[162:165]
	v_mfma_f32_16x16x32_bf16 v[166:169], v[138:141], v[190:193], v[166:169]
	s_setprio 0
	s_add_u32 s2, s10, s56
	s_addc_u32 s3, s11, s57
	s_mov_b32 m0, s66
	v_lshl_add_u64 v[4:5], s[2:3], 0, v[4:5]
	global_load_lds_dwordx4 v[4:5], off
	v_lshl_add_u64 v[4:5], s[2:3], 0, v[6:7]
	s_mov_b32 m0, s65
	s_nop 0
	global_load_lds_dwordx4 v[4:5], off
	s_waitcnt vmcnt(6)
	s_setprio 1
	v_mfma_f32_16x16x32_bf16 v[4:7], v[214:217], v[142:145], v[26:29]
	v_mfma_f32_16x16x32_bf16 v[26:29], v[222:225], v[142:145], v[30:33]
	v_mfma_f32_16x16x32_bf16 v[30:33], v[214:217], v[174:177], v[66:69]
	v_mfma_f32_16x16x32_bf16 v[66:69], v[222:225], v[174:177], v[110:113]
	v_mfma_f32_16x16x32_bf16 v[110:113], v[214:217], v[182:185], v[114:117]
	v_mfma_f32_16x16x32_bf16 v[114:117], v[222:225], v[182:185], v[122:125]
	v_mfma_f32_16x16x32_bf16 v[102:105], v[214:217], v[194:197], v[102:105]
	v_mfma_f32_16x16x32_bf16 v[106:109], v[222:225], v[194:197], v[106:109]
	v_mfma_f32_16x16x32_bf16 v[4:7], v[218:221], v[146:149], v[4:7]
	v_mfma_f32_16x16x32_bf16 v[26:29], v[226:229], v[146:149], v[26:29]
	v_mfma_f32_16x16x32_bf16 v[30:33], v[218:221], v[178:181], v[30:33]
	v_mfma_f32_16x16x32_bf16 v[66:69], v[226:229], v[178:181], v[66:69]
	v_mfma_f32_16x16x32_bf16 v[110:113], v[218:221], v[190:193], v[110:113]
	v_mfma_f32_16x16x32_bf16 v[114:117], v[226:229], v[190:193], v[114:117]
	v_mfma_f32_16x16x32_bf16 v[102:105], v[218:221], v[198:201], v[102:105]
	v_mfma_f32_16x16x32_bf16 v[106:109], v[226:229], v[198:201], v[106:109]
	s_setprio 0
	v_readlane_b32 s2, v255, 19
	s_add_u32 s2, s2, s40
	v_readlane_b32 s3, v255, 20
	s_addc_u32 s3, s3, s41
	s_mov_b32 m0, s90
	v_lshl_add_u64 v[0:1], s[2:3], 0, v[0:1]
	s_barrier
	ds_read_b128 v[122:125], v16
	ds_read_b128 v[126:129], v16 offset:1024
	ds_read_b128 v[130:133], v16 offset:2048
	ds_read_b128 v[134:137], v16 offset:3072
	ds_read_b128 v[138:141], v12
	ds_read_b128 v[142:145], v12 offset:1024
	ds_read_b128 v[146:149], v12 offset:2048
	ds_read_b128 v[170:173], v12 offset:3072
	ds_read_b128 v[174:177], v12 offset:4096
	ds_read_b128 v[178:181], v12 offset:5120
	ds_read_b128 v[182:185], v12 offset:6144
	ds_read_b128 v[190:193], v12 offset:7168
	global_load_lds_dwordx4 v[0:1], off
	v_lshl_add_u64 v[0:1], s[2:3], 0, v[2:3]
	s_mov_b32 m0, s53
	s_nop 0
	global_load_lds_dwordx4 v[0:1], off
	s_barrier
	s_waitcnt lgkmcnt(0)
	s_setprio 1
	s_waitcnt lgkmcnt(0)
	v_mfma_f32_16x16x32_bf16 v[0:3], v[122:125], v[138:141], v[70:73]
	v_mfma_f32_16x16x32_bf16 v[70:73], v[130:133], v[138:141], v[74:77]
	v_mfma_f32_16x16x32_bf16 v[74:77], v[122:125], v[146:149], v[78:81]
	v_mfma_f32_16x16x32_bf16 v[78:81], v[130:133], v[146:149], v[82:85]
	v_mfma_f32_16x16x32_bf16 v[82:85], v[122:125], v[174:177], v[86:89]
	v_mfma_f32_16x16x32_bf16 v[86:89], v[130:133], v[174:177], v[90:93]
	v_mfma_f32_16x16x32_bf16 v[90:93], v[122:125], v[182:185], v[94:97]
	v_mfma_f32_16x16x32_bf16 v[194:197], v[126:129], v[190:193], v[90:93]
	v_mfma_f32_16x16x32_bf16 v[90:93], v[130:133], v[182:185], v[98:101]
	v_mfma_f32_16x16x32_bf16 v[0:3], v[126:129], v[142:145], v[0:3]
	v_mfma_f32_16x16x32_bf16 v[70:73], v[134:137], v[142:145], v[70:73]
	v_mfma_f32_16x16x32_bf16 v[74:77], v[126:129], v[170:173], v[74:77]
	v_mfma_f32_16x16x32_bf16 v[78:81], v[134:137], v[170:173], v[78:81]
	v_mfma_f32_16x16x32_bf16 v[82:85], v[126:129], v[178:181], v[82:85]
	v_mfma_f32_16x16x32_bf16 v[86:89], v[134:137], v[178:181], v[86:89]
	v_mfma_f32_16x16x32_bf16 v[98:101], v[134:137], v[190:193], v[90:93]
	s_setprio 0
	s_barrier
	s_nop 0
	ds_read_b128 v[90:93], v15
	ds_read_b128 v[94:97], v15 offset:1024
	ds_read_b128 v[198:201], v15 offset:2048
	ds_read_b128 v[214:217], v15 offset:3072
	s_barrier
	s_waitcnt lgkmcnt(0)
	s_setprio 1
	s_waitcnt lgkmcnt(0)
	v_mfma_f32_16x16x32_bf16 v[118:121], v[90:93], v[138:141], v[118:121]
	v_mfma_f32_16x16x32_bf16 v[34:37], v[198:201], v[138:141], v[34:37]
	v_mfma_f32_16x16x32_bf16 v[38:41], v[90:93], v[146:149], v[38:41]
	v_mfma_f32_16x16x32_bf16 v[42:45], v[198:201], v[146:149], v[42:45]
	v_mfma_f32_16x16x32_bf16 v[46:49], v[90:93], v[174:177], v[46:49]
	v_mfma_f32_16x16x32_bf16 v[50:53], v[198:201], v[174:177], v[50:53]
	v_mfma_f32_16x16x32_bf16 v[54:57], v[90:93], v[182:185], v[54:57]
	v_mfma_f32_16x16x32_bf16 v[58:61], v[198:201], v[182:185], v[58:61]
	v_mfma_f32_16x16x32_bf16 v[118:121], v[94:97], v[142:145], v[118:121]
	v_mfma_f32_16x16x32_bf16 v[34:37], v[214:217], v[142:145], v[34:37]
	v_mfma_f32_16x16x32_bf16 v[38:41], v[94:97], v[170:173], v[38:41]
	v_mfma_f32_16x16x32_bf16 v[42:45], v[214:217], v[170:173], v[42:45]
	v_mfma_f32_16x16x32_bf16 v[46:49], v[94:97], v[178:181], v[46:49]
	v_mfma_f32_16x16x32_bf16 v[50:53], v[214:217], v[178:181], v[50:53]
	v_mfma_f32_16x16x32_bf16 v[54:57], v[94:97], v[190:193], v[54:57]
	v_mfma_f32_16x16x32_bf16 v[58:61], v[214:217], v[190:193], v[58:61]
	s_setprio 0
	s_barrier
	ds_read_b128 v[138:141], v12 offset:16384
	ds_read_b128 v[142:145], v12 offset:17408
	ds_read_b128 v[146:149], v12 offset:18432
	ds_read_b128 v[170:173], v12 offset:19456
	ds_read_b128 v[174:177], v12 offset:20480
	ds_read_b128 v[178:181], v12 offset:21504
	ds_read_b128 v[182:185], v12 offset:22528
	ds_read_b128 v[190:193], v12 offset:23552
	s_waitcnt vmcnt(4)
	s_barrier
	s_waitcnt lgkmcnt(0)
	s_setprio 1
	s_waitcnt lgkmcnt(0)
	v_mfma_f32_16x16x32_bf16 v[8:11], v[122:125], v[138:141], v[8:11]
	v_mfma_f32_16x16x32_bf16 v[16:19], v[122:125], v[182:185], v[18:21]
	v_mfma_f32_16x16x32_bf16 v[20:23], v[130:133], v[182:185], v[22:25]
	v_mfma_f32_16x16x32_bf16 v[8:11], v[126:129], v[142:145], v[8:11]
	v_mfma_f32_16x16x32_bf16 v[150:153], v[130:133], v[138:141], v[150:153]
	v_mfma_f32_16x16x32_bf16 v[154:157], v[122:125], v[146:149], v[154:157]
	v_mfma_f32_16x16x32_bf16 v[158:161], v[130:133], v[146:149], v[158:161]
	v_mfma_f32_16x16x32_bf16 v[162:165], v[122:125], v[174:177], v[162:165]
	v_mfma_f32_16x16x32_bf16 v[166:169], v[130:133], v[174:177], v[166:169]
	v_mfma_f32_16x16x32_bf16 v[16:19], v[126:129], v[190:193], v[16:19]
	v_mfma_f32_16x16x32_bf16 v[20:23], v[134:137], v[190:193], v[20:23]
	v_mfma_f32_16x16x32_bf16 v[150:153], v[134:137], v[142:145], v[150:153]
	v_mfma_f32_16x16x32_bf16 v[154:157], v[126:129], v[170:173], v[154:157]
	v_mfma_f32_16x16x32_bf16 v[158:161], v[134:137], v[170:173], v[158:161]
	v_mfma_f32_16x16x32_bf16 v[162:165], v[126:129], v[178:181], v[162:165]
	v_mfma_f32_16x16x32_bf16 v[166:169], v[134:137], v[178:181], v[166:169]
	s_setprio 0
	s_setprio 1
	v_mfma_f32_16x16x32_bf16 v[24:27], v[198:201], v[138:141], v[26:29]
	v_mfma_f32_16x16x32_bf16 v[130:133], v[214:217], v[142:145], v[24:27]
	v_mfma_f32_16x16x32_bf16 v[24:27], v[90:93], v[146:149], v[30:33]
	v_mfma_f32_16x16x32_bf16 v[134:137], v[94:97], v[170:173], v[24:27]
	v_mfma_f32_16x16x32_bf16 v[24:27], v[198:201], v[146:149], v[66:69]
	v_mfma_f32_16x16x32_bf16 v[4:7], v[90:93], v[138:141], v[4:7]
	v_mfma_f32_16x16x32_bf16 v[138:141], v[214:217], v[170:173], v[24:27]
	v_mfma_f32_16x16x32_bf16 v[24:27], v[90:93], v[174:177], v[110:113]
	v_mfma_f32_16x16x32_bf16 v[4:7], v[94:97], v[142:145], v[4:7]
	v_mfma_f32_16x16x32_bf16 v[142:145], v[94:97], v[178:181], v[24:27]
	v_mfma_f32_16x16x32_bf16 v[24:27], v[198:201], v[174:177], v[114:117]
	v_mfma_f32_16x16x32_bf16 v[146:149], v[214:217], v[178:181], v[24:27]
	v_mfma_f32_16x16x32_bf16 v[24:27], v[90:93], v[182:185], v[102:105]
	v_mfma_f32_16x16x32_bf16 v[170:173], v[94:97], v[190:193], v[24:27]
	v_mfma_f32_16x16x32_bf16 v[24:27], v[198:201], v[182:185], v[106:109]
	v_mfma_f32_16x16x32_bf16 v[174:177], v[214:217], v[190:193], v[24:27]
	s_setprio 0
	s_barrier
	ds_read_b128 v[178:181], v14
	ds_read_b128 v[182:185], v14 offset:1024
	ds_read_b128 v[190:193], v14 offset:2048
	ds_read_b128 v[198:201], v14 offset:3072
	s_nop 0
	ds_read_b128 v[24:27], v12 offset:32768
	ds_read_b128 v[28:31], v12 offset:33792
	ds_read_b128 v[66:69], v12 offset:34816
	ds_read_b128 v[102:105], v12 offset:35840
	ds_read_b128 v[214:217], v12 offset:36864
	ds_read_b128 v[218:221], v12 offset:37888
	ds_read_b128 v[222:225], v12 offset:38912
	ds_read_b128 v[226:229], v12 offset:39936
	s_waitcnt vmcnt(2)
	s_barrier
	s_waitcnt lgkmcnt(0)
	s_setprio 1
	s_waitcnt lgkmcnt(0)
	v_mfma_f32_16x16x32_bf16 v[0:3], v[178:181], v[24:27], v[0:3]
	v_mfma_f32_16x16x32_bf16 v[122:125], v[182:185], v[28:31], v[0:3]
	v_mfma_f32_16x16x32_bf16 v[0:3], v[190:193], v[24:27], v[70:73]
	v_mfma_f32_16x16x32_bf16 v[126:129], v[198:201], v[28:31], v[0:3]
	v_mfma_f32_16x16x32_bf16 v[0:3], v[178:181], v[66:69], v[74:77]
	v_mfma_f32_16x16x32_bf16 v[106:109], v[182:185], v[102:105], v[0:3]
	v_mfma_f32_16x16x32_bf16 v[0:3], v[190:193], v[66:69], v[78:81]
	v_mfma_f32_16x16x32_bf16 v[110:113], v[198:201], v[102:105], v[0:3]
	v_mfma_f32_16x16x32_bf16 v[0:3], v[178:181], v[214:217], v[82:85]
	v_mfma_f32_16x16x32_bf16 v[90:93], v[182:185], v[218:221], v[0:3]
	v_mfma_f32_16x16x32_bf16 v[0:3], v[190:193], v[214:217], v[86:89]
	v_mfma_f32_16x16x32_bf16 v[94:97], v[198:201], v[218:221], v[0:3]
	v_mfma_f32_16x16x32_bf16 v[0:3], v[178:181], v[222:225], v[194:197]
	v_mfma_f32_16x16x32_bf16 v[74:77], v[182:185], v[226:229], v[0:3]
	v_mfma_f32_16x16x32_bf16 v[0:3], v[190:193], v[222:225], v[98:101]
	v_mfma_f32_16x16x32_bf16 v[78:81], v[198:201], v[226:229], v[0:3]
	s_setprio 0
	s_barrier
	s_nop 4
	ds_read_b128 v[0:3], v13
	ds_read_b128 v[194:197], v13 offset:1024
	ds_read_b128 v[230:233], v13 offset:2048
	ds_read_b128 v[234:237], v13 offset:3072
	s_waitcnt vmcnt(0)
	s_barrier
	s_waitcnt lgkmcnt(0)
	s_setprio 1
	s_waitcnt lgkmcnt(0)
	v_mfma_f32_16x16x32_bf16 v[70:73], v[0:3], v[24:27], v[118:121]
	v_mfma_f32_16x16x32_bf16 v[24:27], v[230:233], v[24:27], v[34:37]
	v_mfma_f32_16x16x32_bf16 v[118:121], v[234:237], v[28:31], v[24:27]
	v_mfma_f32_16x16x32_bf16 v[24:27], v[0:3], v[66:69], v[38:41]
	v_mfma_f32_16x16x32_bf16 v[98:101], v[194:197], v[102:105], v[24:27]
	v_mfma_f32_16x16x32_bf16 v[24:27], v[230:233], v[66:69], v[42:45]
	v_mfma_f32_16x16x32_bf16 v[102:105], v[234:237], v[102:105], v[24:27]
	v_mfma_f32_16x16x32_bf16 v[24:27], v[0:3], v[214:217], v[46:49]
	v_mfma_f32_16x16x32_bf16 v[82:85], v[194:197], v[218:221], v[24:27]
	v_mfma_f32_16x16x32_bf16 v[24:27], v[230:233], v[214:217], v[50:53]
	v_mfma_f32_16x16x32_bf16 v[86:89], v[234:237], v[218:221], v[24:27]
	v_mfma_f32_16x16x32_bf16 v[24:27], v[0:3], v[222:225], v[54:57]
	v_mfma_f32_16x16x32_bf16 v[66:69], v[194:197], v[226:229], v[24:27]
	v_mfma_f32_16x16x32_bf16 v[24:27], v[230:233], v[222:225], v[58:61]
	v_mfma_f32_16x16x32_bf16 v[114:117], v[194:197], v[28:31], v[70:73]
	v_mfma_f32_16x16x32_bf16 v[70:73], v[234:237], v[226:229], v[24:27]
	s_setprio 0
	s_barrier
	ds_read_b128 v[32:35], v12 offset:49152
	ds_read_b128 v[36:39], v12 offset:50176
	ds_read_b128 v[214:217], v12 offset:51200
	ds_read_b128 v[218:221], v12 offset:52224
	ds_read_b128 v[222:225], v12 offset:53248
	ds_read_b128 v[226:229], v12 offset:54272
	ds_read_b128 v[238:241], v12 offset:55296
	ds_read_b128 v[242:245], v12 offset:56320
	s_barrier
	s_waitcnt lgkmcnt(0)
	s_setprio 1
	s_waitcnt lgkmcnt(0)
	v_mfma_f32_16x16x32_bf16 v[8:11], v[178:181], v[32:35], v[8:11]
	v_mfma_f32_16x16x32_bf16 v[56:59], v[182:185], v[36:39], v[8:11]
	v_mfma_f32_16x16x32_bf16 v[8:11], v[190:193], v[32:35], v[150:153]
	v_mfma_f32_16x16x32_bf16 v[60:63], v[198:201], v[36:39], v[8:11]
	v_mfma_f32_16x16x32_bf16 v[8:11], v[178:181], v[214:217], v[154:157]
	v_mfma_f32_16x16x32_bf16 v[40:43], v[182:185], v[218:221], v[8:11]
	v_mfma_f32_16x16x32_bf16 v[8:11], v[190:193], v[214:217], v[158:161]
	v_mfma_f32_16x16x32_bf16 v[44:47], v[198:201], v[218:221], v[8:11]
	v_mfma_f32_16x16x32_bf16 v[8:11], v[178:181], v[222:225], v[162:165]
	v_mfma_f32_16x16x32_bf16 v[24:27], v[182:185], v[226:229], v[8:11]
	v_mfma_f32_16x16x32_bf16 v[8:11], v[190:193], v[222:225], v[166:169]
	v_mfma_f32_16x16x32_bf16 v[28:31], v[198:201], v[226:229], v[8:11]
	v_mfma_f32_16x16x32_bf16 v[8:11], v[178:181], v[238:241], v[16:19]
	v_mfma_f32_16x16x32_bf16 v[12:15], v[190:193], v[238:241], v[20:23]
	v_mfma_f32_16x16x32_bf16 v[8:11], v[182:185], v[242:245], v[8:11]
	v_mfma_f32_16x16x32_bf16 v[12:15], v[198:201], v[242:245], v[12:15]
	s_setprio 0
	s_setprio 1
	v_mfma_f32_16x16x32_bf16 v[4:7], v[0:3], v[32:35], v[4:7]
	v_mfma_f32_16x16x32_bf16 v[48:51], v[194:197], v[36:39], v[4:7]
	v_mfma_f32_16x16x32_bf16 v[4:7], v[230:233], v[32:35], v[130:133]
	v_mfma_f32_16x16x32_bf16 v[52:55], v[234:237], v[36:39], v[4:7]
	v_mfma_f32_16x16x32_bf16 v[4:7], v[0:3], v[214:217], v[134:137]
	v_mfma_f32_16x16x32_bf16 v[32:35], v[194:197], v[218:221], v[4:7]
	v_mfma_f32_16x16x32_bf16 v[4:7], v[230:233], v[214:217], v[138:141]
	v_mfma_f32_16x16x32_bf16 v[36:39], v[234:237], v[218:221], v[4:7]
	v_mfma_f32_16x16x32_bf16 v[4:7], v[0:3], v[222:225], v[142:145]
	v_mfma_f32_16x16x32_bf16 v[16:19], v[194:197], v[226:229], v[4:7]
	v_mfma_f32_16x16x32_bf16 v[4:7], v[230:233], v[222:225], v[146:149]
	v_mfma_f32_16x16x32_bf16 v[0:3], v[0:3], v[238:241], v[170:173]
	v_mfma_f32_16x16x32_bf16 v[20:23], v[234:237], v[226:229], v[4:7]
	v_mfma_f32_16x16x32_bf16 v[4:7], v[194:197], v[242:245], v[0:3]
	v_mfma_f32_16x16x32_bf16 v[0:3], v[230:233], v[238:241], v[174:177]
	v_mfma_f32_16x16x32_bf16 v[0:3], v[234:237], v[242:245], v[0:3]
	s_setprio 0
	v_readlane_b32 s2, v255, 21
	v_readlane_b32 s3, v255, 22
	s_andn2_b64 vcc, exec, s[2:3]
	s_barrier
	s_cbranch_vccnz .LBB0_253
	s_barrier

.LBB0_259:
	s_lshl_b64 s[66:67], s[56:57], 1
	v_readlane_b32 s22, v255, 31
	s_add_u32 s10, s22, s66
	v_readlane_b32 s27, v255, 32
	s_addc_u32 s11, s27, s67
	s_add_i32 s91, 0, 0x18000
	s_add_i32 s90, s91, s58
	v_lshl_add_u64 v[10:11], s[10:11], 0, v[4:5]
	s_mov_b32 m0, s90
	s_add_i32 s17, s90, 0x2000
	v_readlane_b32 vcc_lo, v255, 33
	s_waitcnt vmcnt(4)
	s_barrier
	global_load_lds_dwordx4 v[10:11], off
	v_lshl_add_u64 v[10:11], s[10:11], 0, v[6:7]
	s_add_u32 s10, vcc_lo, s54
	v_readlane_b32 vcc_hi, v255, 34
	s_mov_b32 m0, s17
	s_addc_u32 s11, vcc_hi, s55
	s_add_i32 s49, s61, 0x8000
	global_load_lds_dwordx4 v[10:11], off
	v_lshl_add_u64 v[10:11], s[10:11], 0, v[0:1]
	s_mov_b32 m0, s49
	s_lshl_b64 s[68:69], s[64:65], 1
	global_load_lds_dwordx4 v[10:11], off
	v_lshl_add_u64 v[10:11], s[10:11], 0, v[2:3]
	s_add_i32 s10, s61, 0xa000
	s_add_u32 s56, s22, s68
	s_addc_u32 s57, s27, s69
	s_add_i32 s11, 0, 0x1c000
	s_mov_b32 m0, s10
	s_add_i32 s41, s11, s58
	global_load_lds_dwordx4 v[10:11], off
	v_lshl_add_u64 v[10:11], s[56:57], 0, v[4:5]
	s_mov_b32 m0, s41
	s_add_i32 s22, s41, 0x2000
	global_load_lds_dwordx4 v[10:11], off
	v_lshl_add_u64 v[10:11], s[56:57], 0, v[6:7]
	s_mov_b32 m0, s22
	v_and_b32_e32 v9, 15, v8
	global_load_lds_dwordx4 v[10:11], off
	v_or_b32_e32 v10, s59, v9
	v_and_b32_e32 v11, 48, v8
	v_lshlrev_b32_e32 v8, 2, v8
	v_lshlrev_b32_e32 v12, 6, v10
	s_movk_i32 s52, 0x3c0
	v_lshlrev_b32_e32 v10, 2, v10
	v_lshl_or_b32 v9, v9, 6, v11
	v_and_b32_e32 v8, 32, v8
	v_readlane_b32 s27, v254, 62
	v_and_or_b32 v12, v12, s52, v11
	v_and_b32_e32 v10, 32, v10
	v_bitop3_b32 v9, v9, s27, v8 bitop3:0xde
	s_add_i32 s52, 0, 0x10000
	v_bitop3_b32 v10, v12, s85, v10 bitop3:0xde
	v_add_u32_e32 v64, s52, v9
	s_add_i32 s84, 0, 0x14000
	v_readlane_b32 s87, v255, 37
	s_waitcnt vmcnt(6)
	s_barrier
	v_add_u32_e32 v8, 0, v10
	ds_read_b128 v[10:13], v64
	ds_read_b128 v[14:17], v64 offset:1024
	ds_read_b128 v[18:21], v64 offset:2048
	ds_read_b128 v[22:25], v64 offset:3072
	s_add_u32 s70, s87, s54
	v_readlane_b32 s48, v255, 38
	s_addc_u32 s71, s48, s55
	v_readlane_b32 s27, v255, 35
	s_add_u32 s64, s27, s68
	v_readlane_b32 s86, v255, 36
	s_addc_u32 s65, s86, s69
	v_readlane_b32 s43, v255, 41
	s_add_u32 s56, s43, s54
	v_readlane_b32 s76, v255, 42
	v_add_u32_e32 v186, s84, v9
	v_add_u32_e32 v187, s91, v9
	v_add_u32_e32 v9, s11, v9
	s_addc_u32 s57, s76, s55
	v_readlane_b32 s11, v255, 39
	s_add_u32 s54, s11, s68
	v_readlane_b32 s42, v255, 40
	s_addc_u32 s55, s42, s69
	s_add_u32 s68, vcc_lo, s2
	s_addc_u32 s69, vcc_hi, s3
	s_add_u32 vcc_lo, s11, s66
	s_addc_u32 vcc_hi, s42, s67
	s_add_i32 s91, s61, 0xc000
	v_lshl_add_u64 v[58:59], s[68:69], 0, v[0:1]
	s_mov_b32 m0, s91
	s_add_i32 s11, s61, 0xe000
	ds_read_b128 v[26:29], v8
	ds_read_b128 v[30:33], v8 offset:1024
	ds_read_b128 v[34:37], v8 offset:2048
	ds_read_b128 v[38:41], v8 offset:3072
	ds_read_b128 v[42:45], v8 offset:4096
	ds_read_b128 v[46:49], v8 offset:5120
	ds_read_b128 v[50:53], v8 offset:6144
	ds_read_b128 v[54:57], v8 offset:7168
	global_load_lds_dwordx4 v[58:59], off
	v_lshl_add_u64 v[58:59], s[68:69], 0, v[2:3]
	s_mov_b32 m0, s11
	s_nop 0
	global_load_lds_dwordx4 v[58:59], off
	s_waitcnt lgkmcnt(8)
	s_barrier
	s_waitcnt lgkmcnt(0)
	s_setprio 1
	s_waitcnt lgkmcnt(0)
	v_mfma_f32_16x16x32_bf16 v[58:61], v[10:13], v[26:29], 0
	s_add_u32 s68, s87, s2
	s_addc_u32 s69, s48, s3
	v_mfma_f32_16x16x32_bf16 v[66:69], v[18:21], v[26:29], 0
	v_mfma_f32_16x16x32_bf16 v[70:73], v[10:13], v[34:37], 0
	v_mfma_f32_16x16x32_bf16 v[74:77], v[18:21], v[34:37], 0
	v_mfma_f32_16x16x32_bf16 v[78:81], v[10:13], v[42:45], 0
	v_mfma_f32_16x16x32_bf16 v[82:85], v[18:21], v[42:45], 0
	v_mfma_f32_16x16x32_bf16 v[86:89], v[10:13], v[50:53], 0
	v_mfma_f32_16x16x32_bf16 v[90:93], v[18:21], v[50:53], 0
	v_mfma_f32_16x16x32_bf16 v[58:61], v[14:17], v[30:33], v[58:61]
	v_mfma_f32_16x16x32_bf16 v[66:69], v[22:25], v[30:33], v[66:69]
	v_mfma_f32_16x16x32_bf16 v[70:73], v[14:17], v[38:41], v[70:73]
	v_mfma_f32_16x16x32_bf16 v[74:77], v[22:25], v[38:41], v[74:77]
	v_mfma_f32_16x16x32_bf16 v[78:81], v[14:17], v[46:49], v[78:81]
	v_mfma_f32_16x16x32_bf16 v[82:85], v[22:25], v[46:49], v[82:85]
	v_mfma_f32_16x16x32_bf16 v[86:89], v[14:17], v[54:57], v[86:89]
	v_mfma_f32_16x16x32_bf16 v[90:93], v[22:25], v[54:57], v[90:93]
	s_setprio 0
	s_barrier
	s_add_u32 s66, s27, s66
	s_addc_u32 s67, s86, s67
	s_add_i32 s52, s52, s58
	v_lshl_add_u64 v[62:63], s[66:67], 0, v[4:5]
	s_mov_b32 m0, s52
	ds_read_b128 v[94:97], v186
	ds_read_b128 v[98:101], v186 offset:1024
	ds_read_b128 v[102:105], v186 offset:2048
	ds_read_b128 v[106:109], v186 offset:3072
	global_load_lds_dwordx4 v[62:63], off
	v_lshl_add_u64 v[62:63], s[66:67], 0, v[6:7]
	s_add_i32 m0, s52, 0x2000
	s_nop 0
	global_load_lds_dwordx4 v[62:63], off
	s_waitcnt lgkmcnt(0)
	s_setprio 1
	s_waitcnt lgkmcnt(0)
	v_mfma_f32_16x16x32_bf16 v[110:113], v[94:97], v[26:29], 0
	v_mfma_f32_16x16x32_bf16 v[26:29], v[102:105], v[26:29], 0
	v_mfma_f32_16x16x32_bf16 v[110:113], v[98:101], v[30:33], v[110:113]
	v_mfma_f32_16x16x32_bf16 v[26:29], v[106:109], v[30:33], v[26:29]
	v_mfma_f32_16x16x32_bf16 v[30:33], v[94:97], v[34:37], 0
	v_mfma_f32_16x16x32_bf16 v[34:37], v[102:105], v[34:37], 0
	v_mfma_f32_16x16x32_bf16 v[30:33], v[98:101], v[38:41], v[30:33]
	v_mfma_f32_16x16x32_bf16 v[34:37], v[106:109], v[38:41], v[34:37]
	v_mfma_f32_16x16x32_bf16 v[38:41], v[94:97], v[42:45], 0
	v_mfma_f32_16x16x32_bf16 v[42:45], v[102:105], v[42:45], 0
	v_mfma_f32_16x16x32_bf16 v[38:41], v[98:101], v[46:49], v[38:41]
	v_mfma_f32_16x16x32_bf16 v[42:45], v[106:109], v[46:49], v[42:45]
	v_mfma_f32_16x16x32_bf16 v[46:49], v[94:97], v[50:53], 0
	v_mfma_f32_16x16x32_bf16 v[50:53], v[102:105], v[50:53], 0
	v_mfma_f32_16x16x32_bf16 v[46:49], v[98:101], v[54:57], v[46:49]
	v_mfma_f32_16x16x32_bf16 v[50:53], v[106:109], v[54:57], v[50:53]
	s_setprio 0
	s_mov_b32 m0, s61
	v_lshl_add_u64 v[62:63], s[70:71], 0, v[0:1]
	s_barrier
	ds_read_b128 v[54:57], v8 offset:16384
	ds_read_b128 v[114:117], v8 offset:17408
	ds_read_b128 v[118:121], v8 offset:18432
	ds_read_b128 v[122:125], v8 offset:19456
	ds_read_b128 v[126:129], v8 offset:20480
	ds_read_b128 v[130:133], v8 offset:21504
	ds_read_b128 v[134:137], v8 offset:22528
	ds_read_b128 v[138:141], v8 offset:23552
	global_load_lds_dwordx4 v[62:63], off
	v_lshl_add_u64 v[62:63], s[70:71], 0, v[2:3]
	s_mov_b32 m0, s50
	s_nop 0
	global_load_lds_dwordx4 v[62:63], off
	s_waitcnt vmcnt(4)
	s_barrier
	s_waitcnt lgkmcnt(0)
	s_setprio 1
	s_waitcnt lgkmcnt(0)
	v_mfma_f32_16x16x32_bf16 v[142:145], v[10:13], v[54:57], 0
	v_mfma_f32_16x16x32_bf16 v[150:153], v[10:13], v[118:121], 0
	v_mfma_f32_16x16x32_bf16 v[158:161], v[10:13], v[126:129], 0
	v_mfma_f32_16x16x32_bf16 v[10:13], v[10:13], v[134:137], 0
	v_mfma_f32_16x16x32_bf16 v[142:145], v[14:17], v[114:117], v[142:145]
	v_mfma_f32_16x16x32_bf16 v[150:153], v[14:17], v[122:125], v[150:153]
	v_mfma_f32_16x16x32_bf16 v[158:161], v[14:17], v[130:133], v[158:161]
	v_mfma_f32_16x16x32_bf16 v[10:13], v[14:17], v[138:141], v[10:13]
	v_mfma_f32_16x16x32_bf16 v[14:17], v[18:21], v[134:137], 0
	v_mfma_f32_16x16x32_bf16 v[146:149], v[18:21], v[54:57], 0
	v_mfma_f32_16x16x32_bf16 v[154:157], v[18:21], v[118:121], 0
	v_mfma_f32_16x16x32_bf16 v[162:165], v[18:21], v[126:129], 0
	v_mfma_f32_16x16x32_bf16 v[14:17], v[22:25], v[138:141], v[14:17]
	v_mfma_f32_16x16x32_bf16 v[146:149], v[22:25], v[114:117], v[146:149]
	v_mfma_f32_16x16x32_bf16 v[154:157], v[22:25], v[122:125], v[154:157]
	v_mfma_f32_16x16x32_bf16 v[162:165], v[22:25], v[130:133], v[162:165]
	s_setprio 0
	s_add_i32 s50, s84, s58
	v_lshl_add_u64 v[18:19], s[64:65], 0, v[4:5]
	s_mov_b32 m0, s50
	s_nop 0
	global_load_lds_dwordx4 v[18:19], off
	v_lshl_add_u64 v[18:19], s[64:65], 0, v[6:7]
	s_add_i32 m0, s50, 0x2000
	s_nop 0
	global_load_lds_dwordx4 v[18:19], off
	s_waitcnt vmcnt(6)
	s_setprio 1
	v_mfma_f32_16x16x32_bf16 v[18:21], v[94:97], v[54:57], 0
	v_mfma_f32_16x16x32_bf16 v[22:25], v[102:105], v[54:57], 0
	v_mfma_f32_16x16x32_bf16 v[18:21], v[98:101], v[114:117], v[18:21]
	v_mfma_f32_16x16x32_bf16 v[22:25], v[106:109], v[114:117], v[22:25]
	v_mfma_f32_16x16x32_bf16 v[54:57], v[94:97], v[118:121], 0
	v_mfma_f32_16x16x32_bf16 v[114:117], v[102:105], v[118:121], 0
	v_mfma_f32_16x16x32_bf16 v[118:121], v[94:97], v[126:129], 0
	v_mfma_f32_16x16x32_bf16 v[94:97], v[94:97], v[134:137], 0
	v_mfma_f32_16x16x32_bf16 v[54:57], v[98:101], v[122:125], v[54:57]
	v_mfma_f32_16x16x32_bf16 v[114:117], v[106:109], v[122:125], v[114:117]
	v_mfma_f32_16x16x32_bf16 v[118:121], v[98:101], v[130:133], v[118:121]
	v_mfma_f32_16x16x32_bf16 v[122:125], v[102:105], v[126:129], 0
	v_mfma_f32_16x16x32_bf16 v[94:97], v[98:101], v[138:141], v[94:97]
	v_mfma_f32_16x16x32_bf16 v[98:101], v[102:105], v[134:137], 0
	v_mfma_f32_16x16x32_bf16 v[122:125], v[106:109], v[130:133], v[122:125]
	v_mfma_f32_16x16x32_bf16 v[98:101], v[106:109], v[138:141], v[98:101]
	s_setprio 0
	s_barrier
	ds_read_b128 v[102:105], v187
	ds_read_b128 v[106:109], v187 offset:1024
	ds_read_b128 v[126:129], v187 offset:2048
	ds_read_b128 v[130:133], v187 offset:3072
	s_mov_b32 m0, s60
	v_lshl_add_u64 v[62:63], s[68:69], 0, v[0:1]
	ds_read_b128 v[134:137], v8 offset:32768
	ds_read_b128 v[138:141], v8 offset:33792
	ds_read_b128 v[166:169], v8 offset:34816
	ds_read_b128 v[170:173], v8 offset:35840
	ds_read_b128 v[174:177], v8 offset:36864
	ds_read_b128 v[178:181], v8 offset:37888
	ds_read_b128 v[182:185], v8 offset:38912
	ds_read_b128 v[190:193], v8 offset:39936
	global_load_lds_dwordx4 v[62:63], off
	v_lshl_add_u64 v[62:63], s[68:69], 0, v[2:3]
	s_mov_b32 m0, s53
	s_nop 0
	global_load_lds_dwordx4 v[62:63], off
	s_waitcnt lgkmcnt(8)
	s_barrier
	s_waitcnt lgkmcnt(0)
	s_setprio 1
	s_waitcnt lgkmcnt(0)
	v_mfma_f32_16x16x32_bf16 v[58:61], v[102:105], v[134:137], v[58:61]
	v_mfma_f32_16x16x32_bf16 v[66:69], v[126:129], v[134:137], v[66:69]
	v_mfma_f32_16x16x32_bf16 v[70:73], v[102:105], v[166:169], v[70:73]
	v_mfma_f32_16x16x32_bf16 v[74:77], v[126:129], v[166:169], v[74:77]
	v_mfma_f32_16x16x32_bf16 v[78:81], v[102:105], v[174:177], v[78:81]
	v_mfma_f32_16x16x32_bf16 v[82:85], v[126:129], v[174:177], v[82:85]
	v_mfma_f32_16x16x32_bf16 v[86:89], v[102:105], v[182:185], v[86:89]
	v_mfma_f32_16x16x32_bf16 v[90:93], v[126:129], v[182:185], v[90:93]
	v_mfma_f32_16x16x32_bf16 v[58:61], v[106:109], v[138:141], v[58:61]
	v_mfma_f32_16x16x32_bf16 v[66:69], v[130:133], v[138:141], v[66:69]
	v_mfma_f32_16x16x32_bf16 v[70:73], v[106:109], v[170:173], v[70:73]
	v_mfma_f32_16x16x32_bf16 v[74:77], v[130:133], v[170:173], v[74:77]
	v_mfma_f32_16x16x32_bf16 v[78:81], v[106:109], v[178:181], v[78:81]
	v_mfma_f32_16x16x32_bf16 v[82:85], v[130:133], v[178:181], v[82:85]
	v_mfma_f32_16x16x32_bf16 v[86:89], v[106:109], v[190:193], v[86:89]
	v_mfma_f32_16x16x32_bf16 v[90:93], v[130:133], v[190:193], v[90:93]
	s_setprio 0
	s_barrier
	s_mov_b32 m0, s90
	v_lshl_add_u64 v[62:63], vcc, 0, v[4:5]
	ds_read_b128 v[194:197], v9
	ds_read_b128 v[198:201], v9 offset:1024
	ds_read_b128 v[214:217], v9 offset:2048
	ds_read_b128 v[218:221], v9 offset:3072
	global_load_lds_dwordx4 v[62:63], off
	v_lshl_add_u64 v[62:63], vcc, 0, v[6:7]
	s_mov_b32 m0, s17
	s_nop 0
	global_load_lds_dwordx4 v[62:63], off
	s_waitcnt lgkmcnt(0)
	s_setprio 1
	s_waitcnt lgkmcnt(0)
	v_mfma_f32_16x16x32_bf16 v[110:113], v[194:197], v[134:137], v[110:113]
	v_mfma_f32_16x16x32_bf16 v[26:29], v[214:217], v[134:137], v[26:29]
	v_mfma_f32_16x16x32_bf16 v[30:33], v[194:197], v[166:169], v[30:33]
	v_mfma_f32_16x16x32_bf16 v[34:37], v[214:217], v[166:169], v[34:37]
	v_mfma_f32_16x16x32_bf16 v[38:41], v[194:197], v[174:177], v[38:41]
	v_mfma_f32_16x16x32_bf16 v[42:45], v[214:217], v[174:177], v[42:45]
	v_mfma_f32_16x16x32_bf16 v[46:49], v[194:197], v[182:185], v[46:49]
	v_mfma_f32_16x16x32_bf16 v[50:53], v[214:217], v[182:185], v[50:53]
	v_mfma_f32_16x16x32_bf16 v[110:113], v[198:201], v[138:141], v[110:113]
	v_mfma_f32_16x16x32_bf16 v[26:29], v[218:221], v[138:141], v[26:29]
	v_mfma_f32_16x16x32_bf16 v[30:33], v[198:201], v[170:173], v[30:33]
	v_mfma_f32_16x16x32_bf16 v[34:37], v[218:221], v[170:173], v[34:37]
	v_mfma_f32_16x16x32_bf16 v[38:41], v[198:201], v[178:181], v[38:41]
	v_mfma_f32_16x16x32_bf16 v[42:45], v[218:221], v[178:181], v[42:45]
	v_mfma_f32_16x16x32_bf16 v[46:49], v[198:201], v[190:193], v[46:49]
	v_mfma_f32_16x16x32_bf16 v[50:53], v[218:221], v[190:193], v[50:53]
	s_setprio 0
	s_mov_b32 m0, s49
	v_lshl_add_u64 v[62:63], s[56:57], 0, v[0:1]
	s_barrier
	ds_read_b128 v[134:137], v8 offset:49152
	ds_read_b128 v[138:141], v8 offset:50176
	ds_read_b128 v[166:169], v8 offset:51200
	ds_read_b128 v[170:173], v8 offset:52224
	ds_read_b128 v[174:177], v8 offset:53248
	ds_read_b128 v[178:181], v8 offset:54272
	ds_read_b128 v[182:185], v8 offset:55296
	ds_read_b128 v[190:193], v8 offset:56320
	global_load_lds_dwordx4 v[62:63], off
	v_lshl_add_u64 v[62:63], s[56:57], 0, v[2:3]
	s_mov_b32 m0, s10
	s_nop 0
	global_load_lds_dwordx4 v[62:63], off
	s_waitcnt vmcnt(4)
	s_barrier
	s_waitcnt lgkmcnt(0)
	s_setprio 1
	s_waitcnt lgkmcnt(0)
	v_mfma_f32_16x16x32_bf16 v[10:13], v[102:105], v[182:185], v[10:13]
	v_mfma_f32_16x16x32_bf16 v[14:17], v[126:129], v[182:185], v[14:17]
	v_mfma_f32_16x16x32_bf16 v[142:145], v[102:105], v[134:137], v[142:145]
	v_mfma_f32_16x16x32_bf16 v[146:149], v[126:129], v[134:137], v[146:149]
	v_mfma_f32_16x16x32_bf16 v[150:153], v[102:105], v[166:169], v[150:153]
	v_mfma_f32_16x16x32_bf16 v[154:157], v[126:129], v[166:169], v[154:157]
	v_mfma_f32_16x16x32_bf16 v[158:161], v[102:105], v[174:177], v[158:161]
	v_mfma_f32_16x16x32_bf16 v[162:165], v[126:129], v[174:177], v[162:165]
	v_mfma_f32_16x16x32_bf16 v[10:13], v[106:109], v[190:193], v[10:13]
	v_mfma_f32_16x16x32_bf16 v[14:17], v[130:133], v[190:193], v[14:17]
	v_mfma_f32_16x16x32_bf16 v[142:145], v[106:109], v[138:141], v[142:145]
	v_mfma_f32_16x16x32_bf16 v[146:149], v[130:133], v[138:141], v[146:149]
	v_mfma_f32_16x16x32_bf16 v[150:153], v[106:109], v[170:173], v[150:153]
	v_mfma_f32_16x16x32_bf16 v[154:157], v[130:133], v[170:173], v[154:157]
	v_mfma_f32_16x16x32_bf16 v[158:161], v[106:109], v[178:181], v[158:161]
	v_mfma_f32_16x16x32_bf16 v[162:165], v[130:133], v[178:181], v[162:165]
	s_setprio 0
	s_mov_b32 m0, s41
	v_lshl_add_u64 v[4:5], s[54:55], 0, v[4:5]
	global_load_lds_dwordx4 v[4:5], off
	v_lshl_add_u64 v[4:5], s[54:55], 0, v[6:7]
	s_mov_b32 m0, s22
	s_nop 0
	global_load_lds_dwordx4 v[4:5], off
	s_waitcnt vmcnt(6)
	s_setprio 1
	v_mfma_f32_16x16x32_bf16 v[4:7], v[194:197], v[134:137], v[18:21]
	v_mfma_f32_16x16x32_bf16 v[18:21], v[214:217], v[134:137], v[22:25]
	v_mfma_f32_16x16x32_bf16 v[22:25], v[194:197], v[166:169], v[54:57]
	v_mfma_f32_16x16x32_bf16 v[54:57], v[214:217], v[166:169], v[114:117]
	v_mfma_f32_16x16x32_bf16 v[102:105], v[194:197], v[174:177], v[118:121]
	v_mfma_f32_16x16x32_bf16 v[106:109], v[214:217], v[174:177], v[122:125]
	v_mfma_f32_16x16x32_bf16 v[94:97], v[194:197], v[182:185], v[94:97]
	v_mfma_f32_16x16x32_bf16 v[98:101], v[214:217], v[182:185], v[98:101]
	v_mfma_f32_16x16x32_bf16 v[4:7], v[198:201], v[138:141], v[4:7]
	v_mfma_f32_16x16x32_bf16 v[18:21], v[218:221], v[138:141], v[18:21]
	v_mfma_f32_16x16x32_bf16 v[22:25], v[198:201], v[170:173], v[22:25]
	v_mfma_f32_16x16x32_bf16 v[54:57], v[218:221], v[170:173], v[54:57]
	v_mfma_f32_16x16x32_bf16 v[102:105], v[198:201], v[178:181], v[102:105]
	v_mfma_f32_16x16x32_bf16 v[106:109], v[218:221], v[178:181], v[106:109]
	v_mfma_f32_16x16x32_bf16 v[94:97], v[198:201], v[190:193], v[94:97]
	v_mfma_f32_16x16x32_bf16 v[98:101], v[218:221], v[190:193], v[98:101]
	s_setprio 0
	s_add_u32 s2, s43, s2
	s_addc_u32 s3, s76, s3
	s_mov_b32 m0, s91
	v_lshl_add_u64 v[0:1], s[2:3], 0, v[0:1]
	s_barrier
	ds_read_b128 v[114:117], v64
	ds_read_b128 v[118:121], v64 offset:1024
	ds_read_b128 v[122:125], v64 offset:2048
	ds_read_b128 v[126:129], v64 offset:3072
	ds_read_b128 v[130:133], v8
	ds_read_b128 v[134:137], v8 offset:1024
	ds_read_b128 v[138:141], v8 offset:2048
	ds_read_b128 v[166:169], v8 offset:3072
	ds_read_b128 v[170:173], v8 offset:4096
	ds_read_b128 v[174:177], v8 offset:5120
	ds_read_b128 v[178:181], v8 offset:6144
	ds_read_b128 v[182:185], v8 offset:7168
	global_load_lds_dwordx4 v[0:1], off
	v_lshl_add_u64 v[0:1], s[2:3], 0, v[2:3]
	s_mov_b32 m0, s11
	s_nop 0
	global_load_lds_dwordx4 v[0:1], off
	s_barrier
	s_waitcnt lgkmcnt(0)
	s_setprio 1
	s_waitcnt lgkmcnt(0)
	v_mfma_f32_16x16x32_bf16 v[0:3], v[114:117], v[130:133], v[58:61]
	v_mfma_f32_16x16x32_bf16 v[58:61], v[122:125], v[130:133], v[66:69]
	v_mfma_f32_16x16x32_bf16 v[66:69], v[114:117], v[138:141], v[70:73]
	v_mfma_f32_16x16x32_bf16 v[70:73], v[122:125], v[138:141], v[74:77]
	v_mfma_f32_16x16x32_bf16 v[74:77], v[114:117], v[170:173], v[78:81]
	v_mfma_f32_16x16x32_bf16 v[78:81], v[122:125], v[170:173], v[82:85]
	v_mfma_f32_16x16x32_bf16 v[82:85], v[114:117], v[178:181], v[86:89]
	v_mfma_f32_16x16x32_bf16 v[86:89], v[122:125], v[178:181], v[90:93]
	v_mfma_f32_16x16x32_bf16 v[0:3], v[118:121], v[134:137], v[0:3]
	v_mfma_f32_16x16x32_bf16 v[58:61], v[126:129], v[134:137], v[58:61]
	v_mfma_f32_16x16x32_bf16 v[66:69], v[118:121], v[166:169], v[66:69]
	v_mfma_f32_16x16x32_bf16 v[70:73], v[126:129], v[166:169], v[70:73]
	v_mfma_f32_16x16x32_bf16 v[74:77], v[118:121], v[174:177], v[74:77]
	v_mfma_f32_16x16x32_bf16 v[78:81], v[126:129], v[174:177], v[78:81]
	v_mfma_f32_16x16x32_bf16 v[82:85], v[118:121], v[182:185], v[82:85]
	v_mfma_f32_16x16x32_bf16 v[90:93], v[126:129], v[182:185], v[86:89]
	s_setprio 0
	s_barrier
	s_nop 0
	ds_read_b128 v[86:89], v186
	ds_read_b128 v[190:193], v186 offset:1024
	ds_read_b128 v[194:197], v186 offset:2048
	ds_read_b128 v[198:201], v186 offset:3072
	s_barrier
	s_waitcnt lgkmcnt(0)
	s_setprio 1
	s_waitcnt lgkmcnt(0)
	v_mfma_f32_16x16x32_bf16 v[26:29], v[194:197], v[130:133], v[26:29]
	v_mfma_f32_16x16x32_bf16 v[30:33], v[86:89], v[138:141], v[30:33]
	v_mfma_f32_16x16x32_bf16 v[34:37], v[194:197], v[138:141], v[34:37]
	v_mfma_f32_16x16x32_bf16 v[38:41], v[86:89], v[170:173], v[38:41]
	v_mfma_f32_16x16x32_bf16 v[42:45], v[194:197], v[170:173], v[42:45]
	v_mfma_f32_16x16x32_bf16 v[46:49], v[86:89], v[178:181], v[46:49]
	v_mfma_f32_16x16x32_bf16 v[50:53], v[194:197], v[178:181], v[50:53]
	v_mfma_f32_16x16x32_bf16 v[110:113], v[86:89], v[130:133], v[110:113]
	v_mfma_f32_16x16x32_bf16 v[26:29], v[198:201], v[134:137], v[26:29]
	v_mfma_f32_16x16x32_bf16 v[30:33], v[190:193], v[166:169], v[30:33]
	v_mfma_f32_16x16x32_bf16 v[34:37], v[198:201], v[166:169], v[34:37]
	v_mfma_f32_16x16x32_bf16 v[38:41], v[190:193], v[174:177], v[38:41]
	v_mfma_f32_16x16x32_bf16 v[42:45], v[198:201], v[174:177], v[42:45]
	v_mfma_f32_16x16x32_bf16 v[46:49], v[190:193], v[182:185], v[46:49]
	v_mfma_f32_16x16x32_bf16 v[50:53], v[198:201], v[182:185], v[50:53]
	v_mfma_f32_16x16x32_bf16 v[214:217], v[190:193], v[134:137], v[110:113]
	s_setprio 0
	s_barrier
	s_nop 0
	ds_read_b128 v[110:113], v8 offset:16384
	ds_read_b128 v[130:133], v8 offset:17408
	ds_read_b128 v[134:137], v8 offset:18432
	ds_read_b128 v[138:141], v8 offset:19456
	ds_read_b128 v[166:169], v8 offset:20480
	ds_read_b128 v[170:173], v8 offset:21504
	ds_read_b128 v[174:177], v8 offset:22528
	ds_read_b128 v[178:181], v8 offset:23552
	s_waitcnt vmcnt(4)
	s_barrier
	s_waitcnt lgkmcnt(0)
	s_setprio 1
	s_waitcnt lgkmcnt(0)
	v_mfma_f32_16x16x32_bf16 v[10:13], v[114:117], v[174:177], v[10:13]
	v_mfma_f32_16x16x32_bf16 v[142:145], v[114:117], v[110:113], v[142:145]
	v_mfma_f32_16x16x32_bf16 v[146:149], v[122:125], v[110:113], v[146:149]
	v_mfma_f32_16x16x32_bf16 v[150:153], v[114:117], v[134:137], v[150:153]
	v_mfma_f32_16x16x32_bf16 v[154:157], v[122:125], v[134:137], v[154:157]
	v_mfma_f32_16x16x32_bf16 v[158:161], v[114:117], v[166:169], v[158:161]
	v_mfma_f32_16x16x32_bf16 v[162:165], v[122:125], v[166:169], v[162:165]
	v_mfma_f32_16x16x32_bf16 v[10:13], v[118:121], v[178:181], v[10:13]
	v_mfma_f32_16x16x32_bf16 v[14:17], v[122:125], v[174:177], v[14:17]
	v_mfma_f32_16x16x32_bf16 v[142:145], v[118:121], v[130:133], v[142:145]
	v_mfma_f32_16x16x32_bf16 v[146:149], v[126:129], v[130:133], v[146:149]
	v_mfma_f32_16x16x32_bf16 v[150:153], v[118:121], v[138:141], v[150:153]
	v_mfma_f32_16x16x32_bf16 v[154:157], v[126:129], v[138:141], v[154:157]
	v_mfma_f32_16x16x32_bf16 v[158:161], v[118:121], v[170:173], v[158:161]
	v_mfma_f32_16x16x32_bf16 v[162:165], v[126:129], v[170:173], v[162:165]
	v_mfma_f32_16x16x32_bf16 v[182:185], v[126:129], v[178:181], v[14:17]
	s_setprio 0
	s_setprio 1
	v_mfma_f32_16x16x32_bf16 v[4:7], v[86:89], v[110:113], v[4:7]
	v_mfma_f32_16x16x32_bf16 v[14:17], v[194:197], v[110:113], v[18:21]
	v_mfma_f32_16x16x32_bf16 v[54:57], v[194:197], v[134:137], v[54:57]
	v_mfma_f32_16x16x32_bf16 v[4:7], v[190:193], v[130:133], v[4:7]
	v_mfma_f32_16x16x32_bf16 v[16:19], v[198:201], v[130:133], v[14:17]
	v_mfma_f32_16x16x32_bf16 v[130:133], v[198:201], v[138:141], v[54:57]
	v_mfma_f32_16x16x32_bf16 v[54:57], v[86:89], v[166:169], v[102:105]
	v_mfma_f32_16x16x32_bf16 v[20:23], v[86:89], v[134:137], v[22:25]
	v_mfma_f32_16x16x32_bf16 v[134:137], v[190:193], v[170:173], v[54:57]
	v_mfma_f32_16x16x32_bf16 v[54:57], v[194:197], v[166:169], v[106:109]
	v_mfma_f32_16x16x32_bf16 v[20:23], v[190:193], v[138:141], v[20:23]
	v_mfma_f32_16x16x32_bf16 v[138:141], v[198:201], v[170:173], v[54:57]
	v_mfma_f32_16x16x32_bf16 v[54:57], v[86:89], v[174:177], v[94:97]
	v_mfma_f32_16x16x32_bf16 v[166:169], v[190:193], v[178:181], v[54:57]
	v_mfma_f32_16x16x32_bf16 v[54:57], v[194:197], v[174:177], v[98:101]
	v_mfma_f32_16x16x32_bf16 v[170:173], v[198:201], v[178:181], v[54:57]
	s_setprio 0
	s_barrier
	ds_read_b128 v[174:177], v187
	ds_read_b128 v[178:181], v187 offset:1024
	ds_read_b128 v[190:193], v187 offset:2048
	ds_read_b128 v[194:197], v187 offset:3072
	s_nop 0
	ds_read_b128 v[54:57], v8 offset:32768
	ds_read_b128 v[98:101], v8 offset:33792
	ds_read_b128 v[198:201], v8 offset:34816
	ds_read_b128 v[218:221], v8 offset:35840
	ds_read_b128 v[222:225], v8 offset:36864
	ds_read_b128 v[226:229], v8 offset:37888
	ds_read_b128 v[230:233], v8 offset:38912
	ds_read_b128 v[234:237], v8 offset:39936
	s_waitcnt vmcnt(2)
	s_barrier
	s_waitcnt lgkmcnt(0)
	s_setprio 1
	s_waitcnt lgkmcnt(0)
	v_mfma_f32_16x16x32_bf16 v[0:3], v[174:177], v[54:57], v[0:3]
	v_mfma_f32_16x16x32_bf16 v[126:129], v[178:181], v[98:101], v[0:3]
	v_mfma_f32_16x16x32_bf16 v[0:3], v[190:193], v[54:57], v[58:61]
	v_mfma_f32_16x16x32_bf16 v[122:125], v[194:197], v[98:101], v[0:3]
	v_mfma_f32_16x16x32_bf16 v[0:3], v[174:177], v[198:201], v[66:69]
	v_mfma_f32_16x16x32_bf16 v[110:113], v[178:181], v[218:221], v[0:3]
	v_mfma_f32_16x16x32_bf16 v[0:3], v[190:193], v[198:201], v[70:73]
	v_mfma_f32_16x16x32_bf16 v[102:105], v[194:197], v[218:221], v[0:3]
	v_mfma_f32_16x16x32_bf16 v[0:3], v[174:177], v[222:225], v[74:77]
	v_mfma_f32_16x16x32_bf16 v[94:97], v[178:181], v[226:229], v[0:3]
	v_mfma_f32_16x16x32_bf16 v[0:3], v[190:193], v[222:225], v[78:81]
	v_mfma_f32_16x16x32_bf16 v[86:89], v[194:197], v[226:229], v[0:3]
	v_mfma_f32_16x16x32_bf16 v[0:3], v[174:177], v[230:233], v[82:85]
	v_mfma_f32_16x16x32_bf16 v[78:81], v[178:181], v[234:237], v[0:3]
	v_mfma_f32_16x16x32_bf16 v[0:3], v[190:193], v[230:233], v[90:93]
	v_mfma_f32_16x16x32_bf16 v[70:73], v[194:197], v[234:237], v[0:3]
	s_setprio 0
	s_barrier
	s_nop 4
	ds_read_b128 v[0:3], v9
	ds_read_b128 v[238:241], v9 offset:1024
	ds_read_b128 v[242:245], v9 offset:2048
	ds_read_b128 v[246:249], v9 offset:3072
	s_waitcnt vmcnt(0)
	s_barrier
	s_waitcnt lgkmcnt(0)
	s_setprio 1
	s_waitcnt lgkmcnt(0)
	v_mfma_f32_16x16x32_bf16 v[24:27], v[242:245], v[54:57], v[26:29]
	v_mfma_f32_16x16x32_bf16 v[114:117], v[246:249], v[98:101], v[24:27]
	v_mfma_f32_16x16x32_bf16 v[24:27], v[0:3], v[198:201], v[30:33]
	v_mfma_f32_16x16x32_bf16 v[58:61], v[0:3], v[54:57], v[214:217]
	v_mfma_f32_16x16x32_bf16 v[106:109], v[238:241], v[218:221], v[24:27]
	v_mfma_f32_16x16x32_bf16 v[24:27], v[242:245], v[198:201], v[34:37]
	v_mfma_f32_16x16x32_bf16 v[118:121], v[238:241], v[98:101], v[58:61]
	v_mfma_f32_16x16x32_bf16 v[98:101], v[246:249], v[218:221], v[24:27]
	v_mfma_f32_16x16x32_bf16 v[24:27], v[0:3], v[222:225], v[38:41]
	v_mfma_f32_16x16x32_bf16 v[90:93], v[238:241], v[226:229], v[24:27]
	v_mfma_f32_16x16x32_bf16 v[24:27], v[242:245], v[222:225], v[42:45]
	v_mfma_f32_16x16x32_bf16 v[82:85], v[246:249], v[226:229], v[24:27]
	v_mfma_f32_16x16x32_bf16 v[24:27], v[0:3], v[230:233], v[46:49]
	v_mfma_f32_16x16x32_bf16 v[74:77], v[238:241], v[234:237], v[24:27]
	v_mfma_f32_16x16x32_bf16 v[24:27], v[242:245], v[230:233], v[50:53]
	v_mfma_f32_16x16x32_bf16 v[66:69], v[246:249], v[234:237], v[24:27]
	s_setprio 0
	s_barrier
	ds_read_b128 v[32:35], v8 offset:49152
	ds_read_b128 v[36:39], v8 offset:50176
	ds_read_b128 v[198:201], v8 offset:51200
	ds_read_b128 v[214:217], v8 offset:52224
	ds_read_b128 v[218:221], v8 offset:53248
	ds_read_b128 v[222:225], v8 offset:54272
	ds_read_b128 v[226:229], v8 offset:55296
	ds_read_b128 v[230:233], v8 offset:56320
	s_barrier
	s_waitcnt lgkmcnt(0)
	s_setprio 1
	s_waitcnt lgkmcnt(0)
	v_mfma_f32_16x16x32_bf16 v[24:27], v[174:177], v[32:35], v[142:145]
	v_mfma_f32_16x16x32_bf16 v[60:63], v[178:181], v[36:39], v[24:27]
	v_mfma_f32_16x16x32_bf16 v[24:27], v[190:193], v[32:35], v[146:149]
	v_mfma_f32_16x16x32_bf16 v[56:59], v[194:197], v[36:39], v[24:27]
	v_mfma_f32_16x16x32_bf16 v[24:27], v[174:177], v[198:201], v[150:153]
	v_mfma_f32_16x16x32_bf16 v[44:47], v[178:181], v[214:217], v[24:27]
	v_mfma_f32_16x16x32_bf16 v[24:27], v[190:193], v[198:201], v[154:157]
	v_mfma_f32_16x16x32_bf16 v[40:43], v[194:197], v[214:217], v[24:27]
	v_mfma_f32_16x16x32_bf16 v[24:27], v[174:177], v[218:221], v[158:161]
	v_mfma_f32_16x16x32_bf16 v[8:11], v[174:177], v[226:229], v[10:13]
	v_mfma_f32_16x16x32_bf16 v[28:31], v[178:181], v[222:225], v[24:27]
	v_mfma_f32_16x16x32_bf16 v[24:27], v[190:193], v[218:221], v[162:165]
	v_mfma_f32_16x16x32_bf16 v[12:15], v[178:181], v[230:233], v[8:11]
	v_mfma_f32_16x16x32_bf16 v[8:11], v[190:193], v[226:229], v[182:185]
	v_mfma_f32_16x16x32_bf16 v[24:27], v[194:197], v[222:225], v[24:27]
	v_mfma_f32_16x16x32_bf16 v[8:11], v[194:197], v[230:233], v[8:11]
	s_setprio 0
	s_setprio 1
	v_mfma_f32_16x16x32_bf16 v[4:7], v[0:3], v[32:35], v[4:7]
	v_mfma_f32_16x16x32_bf16 v[52:55], v[238:241], v[36:39], v[4:7]
	v_mfma_f32_16x16x32_bf16 v[4:7], v[242:245], v[32:35], v[16:19]
	v_mfma_f32_16x16x32_bf16 v[48:51], v[246:249], v[36:39], v[4:7]
	v_mfma_f32_16x16x32_bf16 v[4:7], v[0:3], v[198:201], v[20:23]
	v_mfma_f32_16x16x32_bf16 v[36:39], v[238:241], v[214:217], v[4:7]
	v_mfma_f32_16x16x32_bf16 v[4:7], v[242:245], v[198:201], v[130:133]
	v_mfma_f32_16x16x32_bf16 v[32:35], v[246:249], v[214:217], v[4:7]
	v_mfma_f32_16x16x32_bf16 v[4:7], v[0:3], v[218:221], v[134:137]
	v_mfma_f32_16x16x32_bf16 v[20:23], v[238:241], v[222:225], v[4:7]
	v_mfma_f32_16x16x32_bf16 v[4:7], v[242:245], v[218:221], v[138:141]
	v_mfma_f32_16x16x32_bf16 v[0:3], v[0:3], v[226:229], v[166:169]
	v_mfma_f32_16x16x32_bf16 v[16:19], v[246:249], v[222:225], v[4:7]
	v_mfma_f32_16x16x32_bf16 v[4:7], v[238:241], v[230:233], v[0:3]
	v_mfma_f32_16x16x32_bf16 v[0:3], v[242:245], v[226:229], v[170:173]
	v_mfma_f32_16x16x32_bf16 v[0:3], v[246:249], v[230:233], v[0:3]
	s_setprio 0
	v_readlane_b32 s2, v255, 21
	v_readlane_b32 s3, v255, 22
	s_andn2_b64 vcc, exec, s[2:3]
	s_barrier
	s_cbranch_vccnz .LBB0_261
	s_barrier

.LBB0_265:
	s_lshl_b64 s[66:67], s[54:55], 1
	v_readlane_b32 s22, v255, 31
	s_add_u32 s10, s22, s66
	v_readlane_b32 s27, v255, 32
	s_addc_u32 s11, s27, s67
	s_add_i32 s68, 0, 0x18000
	s_add_i32 s17, s68, s58
	v_lshl_add_u64 v[10:11], s[10:11], 0, v[4:5]
	s_mov_b32 m0, s17
	s_add_i32 s90, s17, 0x2000
	v_readlane_b32 s69, v255, 33
	s_waitcnt vmcnt(4)
	s_barrier
	global_load_lds_dwordx4 v[10:11], off
	v_lshl_add_u64 v[10:11], s[10:11], 0, v[6:7]
	s_add_u32 s10, s69, s2
	v_readlane_b32 s91, v255, 34
	s_mov_b32 m0, s90
	s_addc_u32 s11, s91, s3
	s_add_i32 s49, s61, 0x8000
	global_load_lds_dwordx4 v[10:11], off
	v_lshl_add_u64 v[10:11], s[10:11], 0, v[0:1]
	s_mov_b32 m0, s49
	s_lshl_b64 s[56:57], s[56:57], 1
	global_load_lds_dwordx4 v[10:11], off
	v_lshl_add_u64 v[10:11], s[10:11], 0, v[2:3]
	s_add_i32 s10, s61, 0xa000
	s_add_u32 s54, s22, s56
	s_addc_u32 s55, s27, s57
	s_add_i32 s11, 0, 0x1c000
	s_mov_b32 m0, s10
	s_add_i32 s41, s11, s58
	global_load_lds_dwordx4 v[10:11], off
	v_lshl_add_u64 v[10:11], s[54:55], 0, v[4:5]
	s_mov_b32 m0, s41
	s_add_i32 s22, s41, 0x2000
	global_load_lds_dwordx4 v[10:11], off
	v_lshl_add_u64 v[10:11], s[54:55], 0, v[6:7]
	s_mov_b32 m0, s22
	v_and_b32_e32 v9, 15, v8
	global_load_lds_dwordx4 v[10:11], off
	v_or_b32_e32 v10, s59, v9
	v_and_b32_e32 v11, 48, v8
	v_lshlrev_b32_e32 v8, 2, v8
	v_lshlrev_b32_e32 v12, 6, v10
	s_movk_i32 s52, 0x3c0
	v_lshlrev_b32_e32 v10, 2, v10
	v_lshl_or_b32 v9, v9, 6, v11
	v_and_b32_e32 v8, 32, v8
	v_readlane_b32 s27, v254, 62
	v_and_or_b32 v12, v12, s52, v11
	v_and_b32_e32 v10, 32, v10
	v_bitop3_b32 v9, v9, s27, v8 bitop3:0xde
	s_add_i32 vcc_lo, 0, 0x10000
	v_bitop3_b32 v10, v12, s85, v10 bitop3:0xde
	v_add_u32_e32 v64, vcc_lo, v9
	s_add_i32 vcc_hi, 0, 0x14000
	v_readlane_b32 s86, v255, 37
	s_waitcnt vmcnt(6)
	s_barrier
	v_add_u32_e32 v8, 0, v10
	ds_read_b128 v[10:13], v64
	ds_read_b128 v[14:17], v64 offset:1024
	ds_read_b128 v[18:21], v64 offset:2048
	ds_read_b128 v[22:25], v64 offset:3072
	s_add_u32 s70, s86, s2
	v_readlane_b32 s87, v255, 38
	s_addc_u32 s71, s87, s3
	v_readlane_b32 s27, v255, 35
	s_add_u32 s64, s27, s56
	v_readlane_b32 s52, v255, 36
	s_addc_u32 s65, s52, s57
	v_readlane_b32 s43, v255, 41
	s_add_u32 s54, s43, s2
	v_readlane_b32 s76, v255, 42
	v_add_u32_e32 v186, vcc_hi, v9
	v_add_u32_e32 v187, s68, v9
	v_add_u32_e32 v9, s11, v9
	s_addc_u32 s55, s76, s3
	v_readlane_b32 s11, v255, 39
	s_add_u32 s2, s11, s56
	v_readlane_b32 s42, v255, 40
	s_addc_u32 s3, s42, s57
	s_add_u32 s68, s69, s0
	s_addc_u32 s69, s91, s1
	s_add_u32 s56, s11, s66
	s_addc_u32 s57, s42, s67
	s_add_i32 s91, s61, 0xc000
	v_lshl_add_u64 v[58:59], s[68:69], 0, v[0:1]
	s_mov_b32 m0, s91
	s_add_i32 s11, s61, 0xe000
	ds_read_b128 v[26:29], v8
	ds_read_b128 v[30:33], v8 offset:1024
	ds_read_b128 v[34:37], v8 offset:2048
	ds_read_b128 v[38:41], v8 offset:3072
	ds_read_b128 v[42:45], v8 offset:4096
	ds_read_b128 v[46:49], v8 offset:5120
	ds_read_b128 v[50:53], v8 offset:6144
	ds_read_b128 v[54:57], v8 offset:7168
	global_load_lds_dwordx4 v[58:59], off
	v_lshl_add_u64 v[58:59], s[68:69], 0, v[2:3]
	s_mov_b32 m0, s11
	s_nop 0
	global_load_lds_dwordx4 v[58:59], off
	s_waitcnt lgkmcnt(8)
	s_barrier
	s_waitcnt lgkmcnt(0)
	s_setprio 1
	s_waitcnt lgkmcnt(0)
	v_mfma_f32_16x16x32_bf16 v[58:61], v[10:13], v[26:29], 0
	s_add_u32 s68, s86, s0
	s_addc_u32 s69, s87, s1
	v_mfma_f32_16x16x32_bf16 v[66:69], v[18:21], v[26:29], 0
	v_mfma_f32_16x16x32_bf16 v[70:73], v[10:13], v[34:37], 0
	v_mfma_f32_16x16x32_bf16 v[74:77], v[18:21], v[34:37], 0
	v_mfma_f32_16x16x32_bf16 v[78:81], v[10:13], v[42:45], 0
	v_mfma_f32_16x16x32_bf16 v[82:85], v[18:21], v[42:45], 0
	v_mfma_f32_16x16x32_bf16 v[86:89], v[10:13], v[50:53], 0
	v_mfma_f32_16x16x32_bf16 v[90:93], v[18:21], v[50:53], 0
	v_mfma_f32_16x16x32_bf16 v[58:61], v[14:17], v[30:33], v[58:61]
	v_mfma_f32_16x16x32_bf16 v[66:69], v[22:25], v[30:33], v[66:69]
	v_mfma_f32_16x16x32_bf16 v[70:73], v[14:17], v[38:41], v[70:73]
	v_mfma_f32_16x16x32_bf16 v[74:77], v[22:25], v[38:41], v[74:77]
	v_mfma_f32_16x16x32_bf16 v[78:81], v[14:17], v[46:49], v[78:81]
	v_mfma_f32_16x16x32_bf16 v[82:85], v[22:25], v[46:49], v[82:85]
	v_mfma_f32_16x16x32_bf16 v[86:89], v[14:17], v[54:57], v[86:89]
	v_mfma_f32_16x16x32_bf16 v[90:93], v[22:25], v[54:57], v[90:93]
	s_setprio 0
	s_barrier
	s_add_u32 s66, s27, s66
	s_addc_u32 s67, s52, s67
	s_add_i32 vcc_lo, vcc_lo, s58
	v_lshl_add_u64 v[62:63], s[66:67], 0, v[4:5]
	s_mov_b32 m0, vcc_lo
	ds_read_b128 v[94:97], v186
	ds_read_b128 v[98:101], v186 offset:1024
	ds_read_b128 v[102:105], v186 offset:2048
	ds_read_b128 v[106:109], v186 offset:3072
	global_load_lds_dwordx4 v[62:63], off
	v_lshl_add_u64 v[62:63], s[66:67], 0, v[6:7]
	s_add_i32 m0, vcc_lo, 0x2000
	s_nop 0
	global_load_lds_dwordx4 v[62:63], off
	s_waitcnt lgkmcnt(0)
	s_setprio 1
	s_waitcnt lgkmcnt(0)
	v_mfma_f32_16x16x32_bf16 v[110:113], v[94:97], v[26:29], 0
	v_mfma_f32_16x16x32_bf16 v[26:29], v[102:105], v[26:29], 0
	v_mfma_f32_16x16x32_bf16 v[110:113], v[98:101], v[30:33], v[110:113]
	v_mfma_f32_16x16x32_bf16 v[26:29], v[106:109], v[30:33], v[26:29]
	v_mfma_f32_16x16x32_bf16 v[30:33], v[94:97], v[34:37], 0
	v_mfma_f32_16x16x32_bf16 v[34:37], v[102:105], v[34:37], 0
	v_mfma_f32_16x16x32_bf16 v[30:33], v[98:101], v[38:41], v[30:33]
	v_mfma_f32_16x16x32_bf16 v[34:37], v[106:109], v[38:41], v[34:37]
	v_mfma_f32_16x16x32_bf16 v[38:41], v[94:97], v[42:45], 0
	v_mfma_f32_16x16x32_bf16 v[42:45], v[102:105], v[42:45], 0
	v_mfma_f32_16x16x32_bf16 v[38:41], v[98:101], v[46:49], v[38:41]
	v_mfma_f32_16x16x32_bf16 v[42:45], v[106:109], v[46:49], v[42:45]
	v_mfma_f32_16x16x32_bf16 v[46:49], v[94:97], v[50:53], 0
	v_mfma_f32_16x16x32_bf16 v[50:53], v[102:105], v[50:53], 0
	v_mfma_f32_16x16x32_bf16 v[46:49], v[98:101], v[54:57], v[46:49]
	v_mfma_f32_16x16x32_bf16 v[50:53], v[106:109], v[54:57], v[50:53]
	s_setprio 0
	s_mov_b32 m0, s61
	v_lshl_add_u64 v[62:63], s[70:71], 0, v[0:1]
	s_barrier
	ds_read_b128 v[54:57], v8 offset:16384
	ds_read_b128 v[114:117], v8 offset:17408
	ds_read_b128 v[118:121], v8 offset:18432
	ds_read_b128 v[122:125], v8 offset:19456
	ds_read_b128 v[126:129], v8 offset:20480
	ds_read_b128 v[130:133], v8 offset:21504
	ds_read_b128 v[134:137], v8 offset:22528
	ds_read_b128 v[138:141], v8 offset:23552
	global_load_lds_dwordx4 v[62:63], off
	v_lshl_add_u64 v[62:63], s[70:71], 0, v[2:3]
	s_mov_b32 m0, s50
	s_nop 0
	global_load_lds_dwordx4 v[62:63], off
	s_waitcnt vmcnt(4)
	s_barrier
	s_waitcnt lgkmcnt(0)
	s_setprio 1
	s_waitcnt lgkmcnt(0)
	v_mfma_f32_16x16x32_bf16 v[142:145], v[10:13], v[54:57], 0
	v_mfma_f32_16x16x32_bf16 v[150:153], v[10:13], v[118:121], 0
	v_mfma_f32_16x16x32_bf16 v[158:161], v[10:13], v[126:129], 0
	v_mfma_f32_16x16x32_bf16 v[10:13], v[10:13], v[134:137], 0
	v_mfma_f32_16x16x32_bf16 v[142:145], v[14:17], v[114:117], v[142:145]
	v_mfma_f32_16x16x32_bf16 v[150:153], v[14:17], v[122:125], v[150:153]
	v_mfma_f32_16x16x32_bf16 v[158:161], v[14:17], v[130:133], v[158:161]
	v_mfma_f32_16x16x32_bf16 v[10:13], v[14:17], v[138:141], v[10:13]
	v_mfma_f32_16x16x32_bf16 v[14:17], v[18:21], v[134:137], 0
	v_mfma_f32_16x16x32_bf16 v[146:149], v[18:21], v[54:57], 0
	v_mfma_f32_16x16x32_bf16 v[154:157], v[18:21], v[118:121], 0
	v_mfma_f32_16x16x32_bf16 v[162:165], v[18:21], v[126:129], 0
	v_mfma_f32_16x16x32_bf16 v[14:17], v[22:25], v[138:141], v[14:17]
	v_mfma_f32_16x16x32_bf16 v[146:149], v[22:25], v[114:117], v[146:149]
	v_mfma_f32_16x16x32_bf16 v[154:157], v[22:25], v[122:125], v[154:157]
	v_mfma_f32_16x16x32_bf16 v[162:165], v[22:25], v[130:133], v[162:165]
	s_setprio 0
	s_add_i32 s50, vcc_hi, s58
	v_lshl_add_u64 v[18:19], s[64:65], 0, v[4:5]
	s_mov_b32 m0, s50
	s_nop 0
	global_load_lds_dwordx4 v[18:19], off
	v_lshl_add_u64 v[18:19], s[64:65], 0, v[6:7]
	s_add_i32 m0, s50, 0x2000
	s_nop 0
	global_load_lds_dwordx4 v[18:19], off
	s_waitcnt vmcnt(6)
	s_setprio 1
	v_mfma_f32_16x16x32_bf16 v[18:21], v[94:97], v[54:57], 0
	v_mfma_f32_16x16x32_bf16 v[22:25], v[102:105], v[54:57], 0
	v_mfma_f32_16x16x32_bf16 v[18:21], v[98:101], v[114:117], v[18:21]
	v_mfma_f32_16x16x32_bf16 v[22:25], v[106:109], v[114:117], v[22:25]
	v_mfma_f32_16x16x32_bf16 v[54:57], v[94:97], v[118:121], 0
	v_mfma_f32_16x16x32_bf16 v[114:117], v[102:105], v[118:121], 0
	v_mfma_f32_16x16x32_bf16 v[118:121], v[94:97], v[126:129], 0
	v_mfma_f32_16x16x32_bf16 v[94:97], v[94:97], v[134:137], 0
	v_mfma_f32_16x16x32_bf16 v[54:57], v[98:101], v[122:125], v[54:57]
	v_mfma_f32_16x16x32_bf16 v[114:117], v[106:109], v[122:125], v[114:117]
	v_mfma_f32_16x16x32_bf16 v[118:121], v[98:101], v[130:133], v[118:121]
	v_mfma_f32_16x16x32_bf16 v[122:125], v[102:105], v[126:129], 0
	v_mfma_f32_16x16x32_bf16 v[94:97], v[98:101], v[138:141], v[94:97]
	v_mfma_f32_16x16x32_bf16 v[98:101], v[102:105], v[134:137], 0
	v_mfma_f32_16x16x32_bf16 v[122:125], v[106:109], v[130:133], v[122:125]
	v_mfma_f32_16x16x32_bf16 v[98:101], v[106:109], v[138:141], v[98:101]
	s_setprio 0
	s_barrier
	ds_read_b128 v[102:105], v187
	ds_read_b128 v[106:109], v187 offset:1024
	ds_read_b128 v[126:129], v187 offset:2048
	ds_read_b128 v[130:133], v187 offset:3072
	s_mov_b32 m0, s60
	v_lshl_add_u64 v[62:63], s[68:69], 0, v[0:1]
	ds_read_b128 v[134:137], v8 offset:32768
	ds_read_b128 v[138:141], v8 offset:33792
	ds_read_b128 v[166:169], v8 offset:34816
	ds_read_b128 v[170:173], v8 offset:35840
	ds_read_b128 v[174:177], v8 offset:36864
	ds_read_b128 v[178:181], v8 offset:37888
	ds_read_b128 v[182:185], v8 offset:38912
	ds_read_b128 v[190:193], v8 offset:39936
	global_load_lds_dwordx4 v[62:63], off
	v_lshl_add_u64 v[62:63], s[68:69], 0, v[2:3]
	s_mov_b32 m0, s53
	s_nop 0
	global_load_lds_dwordx4 v[62:63], off
	s_waitcnt lgkmcnt(8)
	s_barrier
	s_waitcnt lgkmcnt(0)
	s_setprio 1
	s_waitcnt lgkmcnt(0)
	v_mfma_f32_16x16x32_bf16 v[58:61], v[102:105], v[134:137], v[58:61]
	v_mfma_f32_16x16x32_bf16 v[66:69], v[126:129], v[134:137], v[66:69]
	v_mfma_f32_16x16x32_bf16 v[70:73], v[102:105], v[166:169], v[70:73]
	v_mfma_f32_16x16x32_bf16 v[74:77], v[126:129], v[166:169], v[74:77]
	v_mfma_f32_16x16x32_bf16 v[78:81], v[102:105], v[174:177], v[78:81]
	v_mfma_f32_16x16x32_bf16 v[82:85], v[126:129], v[174:177], v[82:85]
	v_mfma_f32_16x16x32_bf16 v[86:89], v[102:105], v[182:185], v[86:89]
	v_mfma_f32_16x16x32_bf16 v[90:93], v[126:129], v[182:185], v[90:93]
	v_mfma_f32_16x16x32_bf16 v[58:61], v[106:109], v[138:141], v[58:61]
	v_mfma_f32_16x16x32_bf16 v[66:69], v[130:133], v[138:141], v[66:69]
	v_mfma_f32_16x16x32_bf16 v[70:73], v[106:109], v[170:173], v[70:73]
	v_mfma_f32_16x16x32_bf16 v[74:77], v[130:133], v[170:173], v[74:77]
	v_mfma_f32_16x16x32_bf16 v[78:81], v[106:109], v[178:181], v[78:81]
	v_mfma_f32_16x16x32_bf16 v[82:85], v[130:133], v[178:181], v[82:85]
	v_mfma_f32_16x16x32_bf16 v[86:89], v[106:109], v[190:193], v[86:89]
	v_mfma_f32_16x16x32_bf16 v[90:93], v[130:133], v[190:193], v[90:93]
	s_setprio 0
	s_barrier
	s_mov_b32 m0, s17
	v_lshl_add_u64 v[62:63], s[56:57], 0, v[4:5]
	ds_read_b128 v[194:197], v9
	ds_read_b128 v[198:201], v9 offset:1024
	ds_read_b128 v[214:217], v9 offset:2048
	ds_read_b128 v[218:221], v9 offset:3072
	global_load_lds_dwordx4 v[62:63], off
	v_lshl_add_u64 v[62:63], s[56:57], 0, v[6:7]
	s_mov_b32 m0, s90
	s_nop 0
	global_load_lds_dwordx4 v[62:63], off
	s_waitcnt lgkmcnt(0)
	s_setprio 1
	s_waitcnt lgkmcnt(0)
	v_mfma_f32_16x16x32_bf16 v[110:113], v[194:197], v[134:137], v[110:113]
	v_mfma_f32_16x16x32_bf16 v[26:29], v[214:217], v[134:137], v[26:29]
	v_mfma_f32_16x16x32_bf16 v[30:33], v[194:197], v[166:169], v[30:33]
	v_mfma_f32_16x16x32_bf16 v[34:37], v[214:217], v[166:169], v[34:37]
	v_mfma_f32_16x16x32_bf16 v[38:41], v[194:197], v[174:177], v[38:41]
	v_mfma_f32_16x16x32_bf16 v[42:45], v[214:217], v[174:177], v[42:45]
	v_mfma_f32_16x16x32_bf16 v[46:49], v[194:197], v[182:185], v[46:49]
	v_mfma_f32_16x16x32_bf16 v[50:53], v[214:217], v[182:185], v[50:53]
	v_mfma_f32_16x16x32_bf16 v[110:113], v[198:201], v[138:141], v[110:113]
	v_mfma_f32_16x16x32_bf16 v[26:29], v[218:221], v[138:141], v[26:29]
	v_mfma_f32_16x16x32_bf16 v[30:33], v[198:201], v[170:173], v[30:33]
	v_mfma_f32_16x16x32_bf16 v[34:37], v[218:221], v[170:173], v[34:37]
	v_mfma_f32_16x16x32_bf16 v[38:41], v[198:201], v[178:181], v[38:41]
	v_mfma_f32_16x16x32_bf16 v[42:45], v[218:221], v[178:181], v[42:45]
	v_mfma_f32_16x16x32_bf16 v[46:49], v[198:201], v[190:193], v[46:49]
	v_mfma_f32_16x16x32_bf16 v[50:53], v[218:221], v[190:193], v[50:53]
	s_setprio 0
	s_mov_b32 m0, s49
	v_lshl_add_u64 v[62:63], s[54:55], 0, v[0:1]
	s_barrier
	ds_read_b128 v[134:137], v8 offset:49152
	ds_read_b128 v[138:141], v8 offset:50176
	ds_read_b128 v[166:169], v8 offset:51200
	ds_read_b128 v[170:173], v8 offset:52224
	ds_read_b128 v[174:177], v8 offset:53248
	ds_read_b128 v[178:181], v8 offset:54272
	ds_read_b128 v[182:185], v8 offset:55296
	ds_read_b128 v[190:193], v8 offset:56320
	global_load_lds_dwordx4 v[62:63], off
	v_lshl_add_u64 v[62:63], s[54:55], 0, v[2:3]
	s_mov_b32 m0, s10
	s_nop 0
	global_load_lds_dwordx4 v[62:63], off
	s_waitcnt vmcnt(4)
	s_barrier
	s_waitcnt lgkmcnt(0)
	s_setprio 1
	s_waitcnt lgkmcnt(0)
	v_mfma_f32_16x16x32_bf16 v[10:13], v[102:105], v[182:185], v[10:13]
	v_mfma_f32_16x16x32_bf16 v[14:17], v[126:129], v[182:185], v[14:17]
	v_mfma_f32_16x16x32_bf16 v[142:145], v[102:105], v[134:137], v[142:145]
	v_mfma_f32_16x16x32_bf16 v[146:149], v[126:129], v[134:137], v[146:149]
	v_mfma_f32_16x16x32_bf16 v[150:153], v[102:105], v[166:169], v[150:153]
	v_mfma_f32_16x16x32_bf16 v[154:157], v[126:129], v[166:169], v[154:157]
	v_mfma_f32_16x16x32_bf16 v[158:161], v[102:105], v[174:177], v[158:161]
	v_mfma_f32_16x16x32_bf16 v[162:165], v[126:129], v[174:177], v[162:165]
	v_mfma_f32_16x16x32_bf16 v[10:13], v[106:109], v[190:193], v[10:13]
	v_mfma_f32_16x16x32_bf16 v[14:17], v[130:133], v[190:193], v[14:17]
	v_mfma_f32_16x16x32_bf16 v[142:145], v[106:109], v[138:141], v[142:145]
	v_mfma_f32_16x16x32_bf16 v[146:149], v[130:133], v[138:141], v[146:149]
	v_mfma_f32_16x16x32_bf16 v[150:153], v[106:109], v[170:173], v[150:153]
	v_mfma_f32_16x16x32_bf16 v[154:157], v[130:133], v[170:173], v[154:157]
	v_mfma_f32_16x16x32_bf16 v[158:161], v[106:109], v[178:181], v[158:161]
	v_mfma_f32_16x16x32_bf16 v[162:165], v[130:133], v[178:181], v[162:165]
	s_setprio 0
	s_mov_b32 m0, s41
	v_lshl_add_u64 v[4:5], s[2:3], 0, v[4:5]
	global_load_lds_dwordx4 v[4:5], off
	v_lshl_add_u64 v[4:5], s[2:3], 0, v[6:7]
	s_mov_b32 m0, s22
	s_nop 0
	global_load_lds_dwordx4 v[4:5], off
	s_waitcnt vmcnt(6)
	s_setprio 1
	v_mfma_f32_16x16x32_bf16 v[4:7], v[194:197], v[134:137], v[18:21]
	v_mfma_f32_16x16x32_bf16 v[18:21], v[214:217], v[134:137], v[22:25]
	v_mfma_f32_16x16x32_bf16 v[22:25], v[194:197], v[166:169], v[54:57]
	v_mfma_f32_16x16x32_bf16 v[54:57], v[214:217], v[166:169], v[114:117]
	v_mfma_f32_16x16x32_bf16 v[102:105], v[194:197], v[174:177], v[118:121]
	v_mfma_f32_16x16x32_bf16 v[106:109], v[214:217], v[174:177], v[122:125]
	v_mfma_f32_16x16x32_bf16 v[94:97], v[194:197], v[182:185], v[94:97]
	v_mfma_f32_16x16x32_bf16 v[98:101], v[214:217], v[182:185], v[98:101]
	v_mfma_f32_16x16x32_bf16 v[4:7], v[198:201], v[138:141], v[4:7]
	v_mfma_f32_16x16x32_bf16 v[18:21], v[218:221], v[138:141], v[18:21]
	v_mfma_f32_16x16x32_bf16 v[22:25], v[198:201], v[170:173], v[22:25]
	v_mfma_f32_16x16x32_bf16 v[54:57], v[218:221], v[170:173], v[54:57]
	v_mfma_f32_16x16x32_bf16 v[102:105], v[198:201], v[178:181], v[102:105]
	v_mfma_f32_16x16x32_bf16 v[106:109], v[218:221], v[178:181], v[106:109]
	v_mfma_f32_16x16x32_bf16 v[94:97], v[198:201], v[190:193], v[94:97]
	v_mfma_f32_16x16x32_bf16 v[98:101], v[218:221], v[190:193], v[98:101]
	s_setprio 0
	s_add_u32 s0, s43, s0
	s_addc_u32 s1, s76, s1
	s_mov_b32 m0, s91
	v_lshl_add_u64 v[0:1], s[0:1], 0, v[0:1]
	s_barrier
	ds_read_b128 v[114:117], v64
	ds_read_b128 v[118:121], v64 offset:1024
	ds_read_b128 v[122:125], v64 offset:2048
	ds_read_b128 v[126:129], v64 offset:3072
	ds_read_b128 v[130:133], v8
	ds_read_b128 v[134:137], v8 offset:1024
	ds_read_b128 v[138:141], v8 offset:2048
	ds_read_b128 v[166:169], v8 offset:3072
	ds_read_b128 v[170:173], v8 offset:4096
	ds_read_b128 v[174:177], v8 offset:5120
	ds_read_b128 v[178:181], v8 offset:6144
	ds_read_b128 v[182:185], v8 offset:7168
	global_load_lds_dwordx4 v[0:1], off
	v_lshl_add_u64 v[0:1], s[0:1], 0, v[2:3]
	s_mov_b32 m0, s11
	s_nop 0
	global_load_lds_dwordx4 v[0:1], off
	s_barrier
	s_waitcnt lgkmcnt(0)
	s_setprio 1
	s_waitcnt lgkmcnt(0)
	v_mfma_f32_16x16x32_bf16 v[0:3], v[114:117], v[130:133], v[58:61]
	v_mfma_f32_16x16x32_bf16 v[58:61], v[122:125], v[130:133], v[66:69]
	v_mfma_f32_16x16x32_bf16 v[66:69], v[114:117], v[138:141], v[70:73]
	v_mfma_f32_16x16x32_bf16 v[70:73], v[122:125], v[138:141], v[74:77]
	v_mfma_f32_16x16x32_bf16 v[74:77], v[114:117], v[170:173], v[78:81]
	v_mfma_f32_16x16x32_bf16 v[78:81], v[122:125], v[170:173], v[82:85]
	v_mfma_f32_16x16x32_bf16 v[82:85], v[114:117], v[178:181], v[86:89]
	v_mfma_f32_16x16x32_bf16 v[190:193], v[118:121], v[182:185], v[82:85]
	v_mfma_f32_16x16x32_bf16 v[82:85], v[122:125], v[178:181], v[90:93]
	v_mfma_f32_16x16x32_bf16 v[0:3], v[118:121], v[134:137], v[0:3]
	v_mfma_f32_16x16x32_bf16 v[58:61], v[126:129], v[134:137], v[58:61]
	v_mfma_f32_16x16x32_bf16 v[66:69], v[118:121], v[166:169], v[66:69]
	v_mfma_f32_16x16x32_bf16 v[70:73], v[126:129], v[166:169], v[70:73]
	v_mfma_f32_16x16x32_bf16 v[74:77], v[118:121], v[174:177], v[74:77]
	v_mfma_f32_16x16x32_bf16 v[78:81], v[126:129], v[174:177], v[78:81]
	v_mfma_f32_16x16x32_bf16 v[90:93], v[126:129], v[182:185], v[82:85]
	s_setprio 0
	s_barrier
	s_nop 0
	ds_read_b128 v[82:85], v186
	ds_read_b128 v[86:89], v186 offset:1024
	ds_read_b128 v[194:197], v186 offset:2048
	ds_read_b128 v[198:201], v186 offset:3072
	s_barrier
	s_waitcnt lgkmcnt(0)
	s_setprio 1
	s_waitcnt lgkmcnt(0)
	v_mfma_f32_16x16x32_bf16 v[110:113], v[82:85], v[130:133], v[110:113]
	v_mfma_f32_16x16x32_bf16 v[26:29], v[194:197], v[130:133], v[26:29]
	v_mfma_f32_16x16x32_bf16 v[30:33], v[82:85], v[138:141], v[30:33]
	v_mfma_f32_16x16x32_bf16 v[34:37], v[194:197], v[138:141], v[34:37]
	v_mfma_f32_16x16x32_bf16 v[38:41], v[82:85], v[170:173], v[38:41]
	v_mfma_f32_16x16x32_bf16 v[42:45], v[194:197], v[170:173], v[42:45]
	v_mfma_f32_16x16x32_bf16 v[46:49], v[82:85], v[178:181], v[46:49]
	v_mfma_f32_16x16x32_bf16 v[50:53], v[194:197], v[178:181], v[50:53]
	v_mfma_f32_16x16x32_bf16 v[110:113], v[86:89], v[134:137], v[110:113]
	v_mfma_f32_16x16x32_bf16 v[26:29], v[198:201], v[134:137], v[26:29]
	v_mfma_f32_16x16x32_bf16 v[30:33], v[86:89], v[166:169], v[30:33]
	v_mfma_f32_16x16x32_bf16 v[34:37], v[198:201], v[166:169], v[34:37]
	v_mfma_f32_16x16x32_bf16 v[38:41], v[86:89], v[174:177], v[38:41]
	v_mfma_f32_16x16x32_bf16 v[42:45], v[198:201], v[174:177], v[42:45]
	v_mfma_f32_16x16x32_bf16 v[46:49], v[86:89], v[182:185], v[46:49]
	v_mfma_f32_16x16x32_bf16 v[50:53], v[198:201], v[182:185], v[50:53]
	s_setprio 0
	s_barrier
	ds_read_b128 v[130:133], v8 offset:16384
	ds_read_b128 v[134:137], v8 offset:17408
	ds_read_b128 v[138:141], v8 offset:18432
	ds_read_b128 v[166:169], v8 offset:19456
	ds_read_b128 v[170:173], v8 offset:20480
	ds_read_b128 v[174:177], v8 offset:21504
	ds_read_b128 v[178:181], v8 offset:22528
	ds_read_b128 v[182:185], v8 offset:23552
	s_waitcnt vmcnt(4)
	s_barrier
	s_waitcnt lgkmcnt(0)
	s_setprio 1
	s_waitcnt lgkmcnt(0)
	v_mfma_f32_16x16x32_bf16 v[10:13], v[114:117], v[178:181], v[10:13]
	v_mfma_f32_16x16x32_bf16 v[142:145], v[114:117], v[130:133], v[142:145]
	v_mfma_f32_16x16x32_bf16 v[146:149], v[122:125], v[130:133], v[146:149]
	v_mfma_f32_16x16x32_bf16 v[150:153], v[114:117], v[138:141], v[150:153]
	v_mfma_f32_16x16x32_bf16 v[154:157], v[122:125], v[138:141], v[154:157]
	v_mfma_f32_16x16x32_bf16 v[158:161], v[114:117], v[170:173], v[158:161]
	v_mfma_f32_16x16x32_bf16 v[162:165], v[122:125], v[170:173], v[162:165]
	v_mfma_f32_16x16x32_bf16 v[10:13], v[118:121], v[182:185], v[10:13]
	v_mfma_f32_16x16x32_bf16 v[14:17], v[122:125], v[178:181], v[14:17]
	v_mfma_f32_16x16x32_bf16 v[142:145], v[118:121], v[134:137], v[142:145]
	v_mfma_f32_16x16x32_bf16 v[146:149], v[126:129], v[134:137], v[146:149]
	v_mfma_f32_16x16x32_bf16 v[150:153], v[118:121], v[166:169], v[150:153]
	v_mfma_f32_16x16x32_bf16 v[154:157], v[126:129], v[166:169], v[154:157]
	v_mfma_f32_16x16x32_bf16 v[158:161], v[118:121], v[174:177], v[158:161]
	v_mfma_f32_16x16x32_bf16 v[162:165], v[126:129], v[174:177], v[162:165]
	v_mfma_f32_16x16x32_bf16 v[214:217], v[126:129], v[182:185], v[14:17]
	s_setprio 0
	s_setprio 1
	v_mfma_f32_16x16x32_bf16 v[14:17], v[194:197], v[130:133], v[18:21]
	v_mfma_f32_16x16x32_bf16 v[4:7], v[82:85], v[130:133], v[4:7]
	v_mfma_f32_16x16x32_bf16 v[130:133], v[198:201], v[134:137], v[14:17]
	v_mfma_f32_16x16x32_bf16 v[14:17], v[82:85], v[138:141], v[22:25]
	v_mfma_f32_16x16x32_bf16 v[4:7], v[86:89], v[134:137], v[4:7]
	v_mfma_f32_16x16x32_bf16 v[134:137], v[86:89], v[166:169], v[14:17]
	v_mfma_f32_16x16x32_bf16 v[14:17], v[194:197], v[138:141], v[54:57]
	v_mfma_f32_16x16x32_bf16 v[138:141], v[198:201], v[166:169], v[14:17]
	v_mfma_f32_16x16x32_bf16 v[14:17], v[82:85], v[170:173], v[102:105]
	v_mfma_f32_16x16x32_bf16 v[166:169], v[86:89], v[174:177], v[14:17]
	v_mfma_f32_16x16x32_bf16 v[14:17], v[194:197], v[170:173], v[106:109]
	v_mfma_f32_16x16x32_bf16 v[170:173], v[198:201], v[174:177], v[14:17]
	v_mfma_f32_16x16x32_bf16 v[14:17], v[82:85], v[178:181], v[94:97]
	v_mfma_f32_16x16x32_bf16 v[174:177], v[86:89], v[182:185], v[14:17]
	v_mfma_f32_16x16x32_bf16 v[14:17], v[194:197], v[178:181], v[98:101]
	v_mfma_f32_16x16x32_bf16 v[178:181], v[198:201], v[182:185], v[14:17]
	s_setprio 0
	s_barrier
	ds_read_b128 v[182:185], v187
	ds_read_b128 v[194:197], v187 offset:1024
	ds_read_b128 v[198:201], v187 offset:2048
	ds_read_b128 v[218:221], v187 offset:3072
	s_nop 0
	ds_read_b128 v[14:17], v8 offset:32768
	ds_read_b128 v[18:21], v8 offset:33792
	ds_read_b128 v[22:25], v8 offset:34816
	ds_read_b128 v[54:57], v8 offset:35840
	ds_read_b128 v[94:97], v8 offset:36864
	ds_read_b128 v[222:225], v8 offset:37888
	ds_read_b128 v[226:229], v8 offset:38912
	ds_read_b128 v[230:233], v8 offset:39936
	s_waitcnt vmcnt(2)
	s_barrier
	s_waitcnt lgkmcnt(0)
	s_setprio 1
	s_waitcnt lgkmcnt(0)
	v_mfma_f32_16x16x32_bf16 v[0:3], v[182:185], v[14:17], v[0:3]
	v_mfma_f32_16x16x32_bf16 v[122:125], v[194:197], v[18:21], v[0:3]
	v_mfma_f32_16x16x32_bf16 v[0:3], v[198:201], v[14:17], v[58:61]
	v_mfma_f32_16x16x32_bf16 v[126:129], v[218:221], v[18:21], v[0:3]
	v_mfma_f32_16x16x32_bf16 v[0:3], v[182:185], v[22:25], v[66:69]
	v_mfma_f32_16x16x32_bf16 v[98:101], v[194:197], v[54:57], v[0:3]
	v_mfma_f32_16x16x32_bf16 v[0:3], v[198:201], v[22:25], v[70:73]
	v_mfma_f32_16x16x32_bf16 v[102:105], v[218:221], v[54:57], v[0:3]
	v_mfma_f32_16x16x32_bf16 v[0:3], v[182:185], v[94:97], v[74:77]
	v_mfma_f32_16x16x32_bf16 v[82:85], v[194:197], v[222:225], v[0:3]
	v_mfma_f32_16x16x32_bf16 v[0:3], v[198:201], v[94:97], v[78:81]
	v_mfma_f32_16x16x32_bf16 v[86:89], v[218:221], v[222:225], v[0:3]
	v_mfma_f32_16x16x32_bf16 v[0:3], v[182:185], v[226:229], v[190:193]
	v_mfma_f32_16x16x32_bf16 v[66:69], v[194:197], v[230:233], v[0:3]
	v_mfma_f32_16x16x32_bf16 v[0:3], v[198:201], v[226:229], v[90:93]
	v_mfma_f32_16x16x32_bf16 v[70:73], v[218:221], v[230:233], v[0:3]
	s_setprio 0
	s_barrier
	s_nop 4
	ds_read_b128 v[0:3], v9
	ds_read_b128 v[190:193], v9 offset:1024
	ds_read_b128 v[234:237], v9 offset:2048
	ds_read_b128 v[238:241], v9 offset:3072
	s_waitcnt vmcnt(0)
	s_barrier
	s_waitcnt lgkmcnt(0)
	s_setprio 1
	s_waitcnt lgkmcnt(0)
	v_mfma_f32_16x16x32_bf16 v[58:61], v[0:3], v[14:17], v[110:113]
	v_mfma_f32_16x16x32_bf16 v[14:17], v[234:237], v[14:17], v[26:29]
	v_mfma_f32_16x16x32_bf16 v[118:121], v[238:241], v[18:21], v[14:17]
	v_mfma_f32_16x16x32_bf16 v[14:17], v[0:3], v[22:25], v[30:33]
	v_mfma_f32_16x16x32_bf16 v[106:109], v[190:193], v[54:57], v[14:17]
	v_mfma_f32_16x16x32_bf16 v[14:17], v[234:237], v[22:25], v[34:37]
	v_mfma_f32_16x16x32_bf16 v[110:113], v[238:241], v[54:57], v[14:17]
	v_mfma_f32_16x16x32_bf16 v[14:17], v[0:3], v[94:97], v[38:41]
	v_mfma_f32_16x16x32_bf16 v[90:93], v[190:193], v[222:225], v[14:17]
	v_mfma_f32_16x16x32_bf16 v[14:17], v[234:237], v[94:97], v[42:45]
	v_mfma_f32_16x16x32_bf16 v[94:97], v[238:241], v[222:225], v[14:17]
	v_mfma_f32_16x16x32_bf16 v[14:17], v[0:3], v[226:229], v[46:49]
	v_mfma_f32_16x16x32_bf16 v[74:77], v[190:193], v[230:233], v[14:17]
	v_mfma_f32_16x16x32_bf16 v[14:17], v[234:237], v[226:229], v[50:53]
	v_mfma_f32_16x16x32_bf16 v[114:117], v[190:193], v[18:21], v[58:61]
	v_mfma_f32_16x16x32_bf16 v[78:81], v[238:241], v[230:233], v[14:17]
	s_setprio 0
	s_barrier
	ds_read_b128 v[24:27], v8 offset:49152
	ds_read_b128 v[28:31], v8 offset:50176
	ds_read_b128 v[44:47], v8 offset:51200
	ds_read_b128 v[222:225], v8 offset:52224
	ds_read_b128 v[226:229], v8 offset:53248
	ds_read_b128 v[230:233], v8 offset:54272
	ds_read_b128 v[242:245], v8 offset:55296
	ds_read_b128 v[246:249], v8 offset:56320
	s_barrier
	s_waitcnt lgkmcnt(0)
	s_setprio 1
	s_waitcnt lgkmcnt(0)
	v_mfma_f32_16x16x32_bf16 v[14:17], v[182:185], v[24:27], v[142:145]
	v_mfma_f32_16x16x32_bf16 v[48:51], v[194:197], v[28:31], v[14:17]
	v_mfma_f32_16x16x32_bf16 v[14:17], v[198:201], v[24:27], v[146:149]
	v_mfma_f32_16x16x32_bf16 v[52:55], v[218:221], v[28:31], v[14:17]
	v_mfma_f32_16x16x32_bf16 v[14:17], v[182:185], v[44:47], v[150:153]
	v_mfma_f32_16x16x32_bf16 v[32:35], v[194:197], v[222:225], v[14:17]
	v_mfma_f32_16x16x32_bf16 v[14:17], v[198:201], v[44:47], v[154:157]
	v_mfma_f32_16x16x32_bf16 v[36:39], v[218:221], v[222:225], v[14:17]
	v_mfma_f32_16x16x32_bf16 v[14:17], v[182:185], v[226:229], v[158:161]
	v_mfma_f32_16x16x32_bf16 v[16:19], v[194:197], v[230:233], v[14:17]
	v_mfma_f32_16x16x32_bf16 v[20:23], v[198:201], v[226:229], v[162:165]
	v_mfma_f32_16x16x32_bf16 v[8:11], v[182:185], v[242:245], v[10:13]
	v_mfma_f32_16x16x32_bf16 v[12:15], v[198:201], v[242:245], v[214:217]
	v_mfma_f32_16x16x32_bf16 v[20:23], v[218:221], v[230:233], v[20:23]
	v_mfma_f32_16x16x32_bf16 v[8:11], v[194:197], v[246:249], v[8:11]
	v_mfma_f32_16x16x32_bf16 v[12:15], v[218:221], v[246:249], v[12:15]
	s_setprio 0
	s_setprio 1
	v_mfma_f32_16x16x32_bf16 v[4:7], v[0:3], v[24:27], v[4:7]
	v_mfma_f32_16x16x32_bf16 v[56:59], v[190:193], v[28:31], v[4:7]
	v_mfma_f32_16x16x32_bf16 v[4:7], v[234:237], v[24:27], v[130:133]
	v_mfma_f32_16x16x32_bf16 v[60:63], v[238:241], v[28:31], v[4:7]
	v_mfma_f32_16x16x32_bf16 v[4:7], v[0:3], v[44:47], v[134:137]
	v_mfma_f32_16x16x32_bf16 v[40:43], v[190:193], v[222:225], v[4:7]
	v_mfma_f32_16x16x32_bf16 v[4:7], v[234:237], v[44:47], v[138:141]
	v_mfma_f32_16x16x32_bf16 v[44:47], v[238:241], v[222:225], v[4:7]
	v_mfma_f32_16x16x32_bf16 v[4:7], v[0:3], v[226:229], v[166:169]
	v_mfma_f32_16x16x32_bf16 v[24:27], v[190:193], v[230:233], v[4:7]
	v_mfma_f32_16x16x32_bf16 v[4:7], v[234:237], v[226:229], v[170:173]
	v_mfma_f32_16x16x32_bf16 v[0:3], v[0:3], v[242:245], v[174:177]
	v_mfma_f32_16x16x32_bf16 v[28:31], v[238:241], v[230:233], v[4:7]
	v_mfma_f32_16x16x32_bf16 v[4:7], v[190:193], v[246:249], v[0:3]
	v_mfma_f32_16x16x32_bf16 v[0:3], v[234:237], v[242:245], v[178:181]
	v_mfma_f32_16x16x32_bf16 v[0:3], v[238:241], v[246:249], v[0:3]
	s_setprio 0
	v_readlane_b32 s0, v255, 21
	v_readlane_b32 s1, v255, 22
	s_andn2_b64 vcc, exec, s[0:1]
	s_barrier
	s_cbranch_vccnz .LBB0_267
	s_barrier

.LBB0_274:
	s_add_i32 s6, 0, 0x18000
	s_add_i32 s40, s6, s58
	v_lshl_add_u64 v[18:19], v[12:13], 0, s[24:25]
	s_mov_b32 m0, s40
	s_add_i32 s17, s40, 0x2000
	s_waitcnt vmcnt(4)
	s_barrier
	global_load_lds_dwordx4 v[18:19], off
	v_lshl_add_u64 v[18:19], v[14:15], 0, s[24:25]
	s_mov_b32 m0, s17
	s_add_i32 s11, s49, 0x8000
	global_load_lds_dwordx4 v[18:19], off
	v_lshl_add_u64 v[18:19], v[8:9], 0, s[24:25]
	s_mov_b32 m0, s11
	s_add_i32 s10, s49, 0xa000
	s_add_i32 s7, 0, 0x1c000
	global_load_lds_dwordx4 v[18:19], off
	v_lshl_add_u64 v[18:19], v[10:11], 0, s[24:25]
	s_mov_b32 m0, s10
	s_add_i32 s3, s7, s58
	global_load_lds_dwordx4 v[18:19], off
	v_lshl_add_u64 v[18:19], v[4:5], 0, s[24:25]
	s_mov_b32 m0, s3
	s_add_i32 s1, s3, 0x2000
	global_load_lds_dwordx4 v[18:19], off
	v_lshl_add_u64 v[18:19], v[6:7], 0, s[24:25]
	s_mov_b32 m0, s1
	v_and_b32_e32 v17, 15, v16
	global_load_lds_dwordx4 v[18:19], off
	v_or_b32_e32 v18, s59, v17
	v_and_b32_e32 v19, 48, v16
	v_lshlrev_b32_e32 v20, 6, v18
	s_movk_i32 s52, 0x3c0
	v_lshlrev_b32_e32 v16, 2, v16
	v_and_or_b32 v20, v20, s52, v19
	v_lshlrev_b32_e32 v18, 2, v18
	v_lshl_or_b32 v17, v17, 6, v19
	v_and_b32_e32 v16, 32, v16
	v_readlane_b32 s52, v254, 62
	v_and_b32_e32 v18, 32, v18
	s_add_i32 s53, 0, 0x10000
	v_bitop3_b32 v32, v17, s52, v16 bitop3:0xde
	v_bitop3_b32 v18, v20, s85, v18 bitop3:0xde
	v_add_u32_e32 v64, s53, v32
	s_waitcnt vmcnt(6)
	s_barrier
	v_add_u32_e32 v252, 0, v18
	ds_read_b128 v[16:19], v64
	ds_read_b128 v[20:23], v64 offset:1024
	ds_read_b128 v[24:27], v64 offset:2048
	ds_read_b128 v[28:31], v64 offset:3072
	s_add_i32 s54, 0, 0x14000
	v_add_u32_e32 v198, s54, v32
	v_add_u32_e32 v199, s6, v32
	v_add_u32_e32 v200, s7, v32
	s_add_i32 s7, s49, 0xc000
	v_lshl_add_u64 v[66:67], v[0:1], 0, s[24:25]
	s_mov_b32 m0, s7
	s_add_i32 s6, s49, 0xe000
	ds_read_b128 v[32:35], v252
	ds_read_b128 v[36:39], v252 offset:1024
	ds_read_b128 v[40:43], v252 offset:2048
	ds_read_b128 v[44:47], v252 offset:3072
	ds_read_b128 v[48:51], v252 offset:4096
	ds_read_b128 v[52:55], v252 offset:5120
	ds_read_b128 v[56:59], v252 offset:6144
	ds_read_b128 v[60:63], v252 offset:7168
	global_load_lds_dwordx4 v[66:67], off
	v_lshl_add_u64 v[66:67], v[2:3], 0, s[24:25]
	s_mov_b32 m0, s6
	s_nop 0
	global_load_lds_dwordx4 v[66:67], off
	s_waitcnt lgkmcnt(8)
	s_barrier
	s_waitcnt lgkmcnt(0)
	s_setprio 1
	s_waitcnt lgkmcnt(0)
	v_mfma_f32_16x16x32_bf16 v[66:69], v[16:19], v[32:35], 0
	v_mfma_f32_16x16x32_bf16 v[70:73], v[24:27], v[32:35], 0
	v_mfma_f32_16x16x32_bf16 v[74:77], v[16:19], v[40:43], 0
	v_mfma_f32_16x16x32_bf16 v[78:81], v[24:27], v[40:43], 0
	v_mfma_f32_16x16x32_bf16 v[82:85], v[16:19], v[48:51], 0
	v_mfma_f32_16x16x32_bf16 v[86:89], v[24:27], v[48:51], 0
	v_mfma_f32_16x16x32_bf16 v[90:93], v[16:19], v[56:59], 0
	v_mfma_f32_16x16x32_bf16 v[94:97], v[24:27], v[56:59], 0
	v_mfma_f32_16x16x32_bf16 v[66:69], v[20:23], v[36:39], v[66:69]
	v_mfma_f32_16x16x32_bf16 v[70:73], v[28:31], v[36:39], v[70:73]
	v_mfma_f32_16x16x32_bf16 v[74:77], v[20:23], v[44:47], v[74:77]
	v_mfma_f32_16x16x32_bf16 v[78:81], v[28:31], v[44:47], v[78:81]
	v_mfma_f32_16x16x32_bf16 v[82:85], v[20:23], v[52:55], v[82:85]
	v_mfma_f32_16x16x32_bf16 v[86:89], v[28:31], v[52:55], v[86:89]
	v_mfma_f32_16x16x32_bf16 v[90:93], v[20:23], v[60:63], v[90:93]
	v_mfma_f32_16x16x32_bf16 v[94:97], v[28:31], v[60:63], v[94:97]
	s_setprio 0
	s_barrier
	s_add_i32 s53, s53, s58
	v_lshl_add_u64 v[114:115], v[12:13], 0, s[28:29]
	s_mov_b32 m0, s53
	ds_read_b128 v[98:101], v198
	ds_read_b128 v[102:105], v198 offset:1024
	ds_read_b128 v[106:109], v198 offset:2048
	ds_read_b128 v[110:113], v198 offset:3072
	global_load_lds_dwordx4 v[114:115], off
	v_lshl_add_u64 v[114:115], v[14:15], 0, s[28:29]
	s_add_i32 m0, s53, 0x2000
	s_nop 0
	global_load_lds_dwordx4 v[114:115], off
	s_waitcnt lgkmcnt(0)
	s_setprio 1
	s_waitcnt lgkmcnt(0)
	v_mfma_f32_16x16x32_bf16 v[114:117], v[98:101], v[32:35], 0
	v_mfma_f32_16x16x32_bf16 v[32:35], v[106:109], v[32:35], 0
	v_mfma_f32_16x16x32_bf16 v[114:117], v[102:105], v[36:39], v[114:117]
	v_mfma_f32_16x16x32_bf16 v[32:35], v[110:113], v[36:39], v[32:35]
	v_mfma_f32_16x16x32_bf16 v[36:39], v[98:101], v[40:43], 0
	v_mfma_f32_16x16x32_bf16 v[40:43], v[106:109], v[40:43], 0
	v_mfma_f32_16x16x32_bf16 v[36:39], v[102:105], v[44:47], v[36:39]
	v_mfma_f32_16x16x32_bf16 v[40:43], v[110:113], v[44:47], v[40:43]
	v_mfma_f32_16x16x32_bf16 v[44:47], v[98:101], v[48:51], 0
	v_mfma_f32_16x16x32_bf16 v[48:51], v[106:109], v[48:51], 0
	v_mfma_f32_16x16x32_bf16 v[44:47], v[102:105], v[52:55], v[44:47]
	v_mfma_f32_16x16x32_bf16 v[48:51], v[110:113], v[52:55], v[48:51]
	v_mfma_f32_16x16x32_bf16 v[52:55], v[98:101], v[56:59], 0
	v_mfma_f32_16x16x32_bf16 v[56:59], v[106:109], v[56:59], 0
	v_mfma_f32_16x16x32_bf16 v[52:55], v[102:105], v[60:63], v[52:55]
	v_mfma_f32_16x16x32_bf16 v[56:59], v[110:113], v[60:63], v[56:59]
	s_setprio 0
	s_mov_b32 m0, s49
	v_lshl_add_u64 v[146:147], v[8:9], 0, s[28:29]
	s_barrier
	ds_read_b128 v[60:63], v252 offset:16384
	ds_read_b128 v[118:121], v252 offset:17408
	ds_read_b128 v[122:125], v252 offset:18432
	ds_read_b128 v[126:129], v252 offset:19456
	ds_read_b128 v[130:133], v252 offset:20480
	ds_read_b128 v[134:137], v252 offset:21504
	ds_read_b128 v[138:141], v252 offset:22528
	ds_read_b128 v[142:145], v252 offset:23552
	global_load_lds_dwordx4 v[146:147], off
	v_lshl_add_u64 v[146:147], v[10:11], 0, s[28:29]
	s_mov_b32 m0, s50
	s_nop 0
	global_load_lds_dwordx4 v[146:147], off
	s_waitcnt vmcnt(4)
	s_barrier
	s_waitcnt lgkmcnt(0)
	s_setprio 1
	s_waitcnt lgkmcnt(0)
	v_mfma_f32_16x16x32_bf16 v[146:149], v[16:19], v[60:63], 0
	v_mfma_f32_16x16x32_bf16 v[154:157], v[16:19], v[122:125], 0
	v_mfma_f32_16x16x32_bf16 v[162:165], v[16:19], v[130:133], 0
	v_mfma_f32_16x16x32_bf16 v[16:19], v[16:19], v[138:141], 0
	v_mfma_f32_16x16x32_bf16 v[146:149], v[20:23], v[118:121], v[146:149]
	v_mfma_f32_16x16x32_bf16 v[154:157], v[20:23], v[126:129], v[154:157]
	v_mfma_f32_16x16x32_bf16 v[162:165], v[20:23], v[134:137], v[162:165]
	v_mfma_f32_16x16x32_bf16 v[16:19], v[20:23], v[142:145], v[16:19]
	v_mfma_f32_16x16x32_bf16 v[20:23], v[24:27], v[138:141], 0
	v_mfma_f32_16x16x32_bf16 v[150:153], v[24:27], v[60:63], 0
	v_mfma_f32_16x16x32_bf16 v[158:161], v[24:27], v[122:125], 0
	v_mfma_f32_16x16x32_bf16 v[166:169], v[24:27], v[130:133], 0
	v_mfma_f32_16x16x32_bf16 v[20:23], v[28:31], v[142:145], v[20:23]
	v_mfma_f32_16x16x32_bf16 v[150:153], v[28:31], v[118:121], v[150:153]
	v_mfma_f32_16x16x32_bf16 v[158:161], v[28:31], v[126:129], v[158:161]
	v_mfma_f32_16x16x32_bf16 v[166:169], v[28:31], v[134:137], v[166:169]
	s_setprio 0
	s_add_i32 s49, s54, s58
	v_lshl_add_u64 v[24:25], v[4:5], 0, s[28:29]
	s_mov_b32 m0, s49
	s_nop 0
	global_load_lds_dwordx4 v[24:25], off
	v_lshl_add_u64 v[24:25], v[6:7], 0, s[28:29]
	s_add_i32 m0, s49, 0x2000
	s_nop 0
	global_load_lds_dwordx4 v[24:25], off
	s_waitcnt vmcnt(6)
	s_setprio 1
	v_mfma_f32_16x16x32_bf16 v[24:27], v[98:101], v[60:63], 0
	v_mfma_f32_16x16x32_bf16 v[28:31], v[106:109], v[60:63], 0
	v_mfma_f32_16x16x32_bf16 v[24:27], v[102:105], v[118:121], v[24:27]
	v_mfma_f32_16x16x32_bf16 v[28:31], v[110:113], v[118:121], v[28:31]
	v_mfma_f32_16x16x32_bf16 v[60:63], v[98:101], v[122:125], 0
	v_mfma_f32_16x16x32_bf16 v[118:121], v[106:109], v[122:125], 0
	v_mfma_f32_16x16x32_bf16 v[122:125], v[98:101], v[130:133], 0
	v_mfma_f32_16x16x32_bf16 v[98:101], v[98:101], v[138:141], 0
	v_mfma_f32_16x16x32_bf16 v[60:63], v[102:105], v[126:129], v[60:63]
	v_mfma_f32_16x16x32_bf16 v[118:121], v[110:113], v[126:129], v[118:121]
	v_mfma_f32_16x16x32_bf16 v[122:125], v[102:105], v[134:137], v[122:125]
	v_mfma_f32_16x16x32_bf16 v[126:129], v[106:109], v[130:133], 0
	v_mfma_f32_16x16x32_bf16 v[98:101], v[102:105], v[142:145], v[98:101]
	v_mfma_f32_16x16x32_bf16 v[102:105], v[106:109], v[138:141], 0
	v_mfma_f32_16x16x32_bf16 v[126:129], v[110:113], v[134:137], v[126:129]
	v_mfma_f32_16x16x32_bf16 v[102:105], v[110:113], v[142:145], v[102:105]
	s_setprio 0
	s_barrier
	ds_read_b128 v[106:109], v199
	ds_read_b128 v[110:113], v199 offset:1024
	ds_read_b128 v[130:133], v199 offset:2048
	ds_read_b128 v[134:137], v199 offset:3072
	s_mov_b32 m0, s41
	v_lshl_add_u64 v[186:187], v[0:1], 0, s[28:29]
	ds_read_b128 v[138:141], v252 offset:32768
	ds_read_b128 v[142:145], v252 offset:33792
	ds_read_b128 v[170:173], v252 offset:34816
	ds_read_b128 v[174:177], v252 offset:35840
	ds_read_b128 v[178:181], v252 offset:36864
	ds_read_b128 v[182:185], v252 offset:37888
	ds_read_b128 v[190:193], v252 offset:38912
	ds_read_b128 v[194:197], v252 offset:39936
	global_load_lds_dwordx4 v[186:187], off
	v_lshl_add_u64 v[186:187], v[2:3], 0, s[28:29]
	s_mov_b32 m0, s22
	s_nop 0
	global_load_lds_dwordx4 v[186:187], off
	s_waitcnt lgkmcnt(8)
	s_barrier
	s_waitcnt lgkmcnt(0)
	s_setprio 1
	s_waitcnt lgkmcnt(0)
	v_mfma_f32_16x16x32_bf16 v[66:69], v[106:109], v[138:141], v[66:69]
	v_mfma_f32_16x16x32_bf16 v[70:73], v[130:133], v[138:141], v[70:73]
	v_mfma_f32_16x16x32_bf16 v[74:77], v[106:109], v[170:173], v[74:77]
	v_mfma_f32_16x16x32_bf16 v[78:81], v[130:133], v[170:173], v[78:81]
	v_mfma_f32_16x16x32_bf16 v[82:85], v[106:109], v[178:181], v[82:85]
	v_mfma_f32_16x16x32_bf16 v[86:89], v[130:133], v[178:181], v[86:89]
	v_mfma_f32_16x16x32_bf16 v[90:93], v[106:109], v[190:193], v[90:93]
	v_mfma_f32_16x16x32_bf16 v[94:97], v[130:133], v[190:193], v[94:97]
	v_mfma_f32_16x16x32_bf16 v[66:69], v[110:113], v[142:145], v[66:69]
	v_mfma_f32_16x16x32_bf16 v[70:73], v[134:137], v[142:145], v[70:73]
	v_mfma_f32_16x16x32_bf16 v[74:77], v[110:113], v[174:177], v[74:77]
	v_mfma_f32_16x16x32_bf16 v[78:81], v[134:137], v[174:177], v[78:81]
	v_mfma_f32_16x16x32_bf16 v[82:85], v[110:113], v[182:185], v[82:85]
	v_mfma_f32_16x16x32_bf16 v[86:89], v[134:137], v[182:185], v[86:89]
	v_mfma_f32_16x16x32_bf16 v[90:93], v[110:113], v[194:197], v[90:93]
	v_mfma_f32_16x16x32_bf16 v[94:97], v[134:137], v[194:197], v[94:97]
	s_setprio 0
	s_barrier
	s_mov_b32 m0, s40
	s_mov_b64 s[40:41], 0x180
	v_lshl_add_u64 v[12:13], v[12:13], 0, s[40:41]
	ds_read_b128 v[214:217], v200
	ds_read_b128 v[218:221], v200 offset:1024
	ds_read_b128 v[222:225], v200 offset:2048
	ds_read_b128 v[226:229], v200 offset:3072
	global_load_lds_dwordx4 v[12:13], off
	v_lshl_add_u64 v[12:13], v[14:15], 0, s[40:41]
	s_mov_b32 m0, s17
	s_nop 0
	global_load_lds_dwordx4 v[12:13], off
	s_waitcnt lgkmcnt(0)
	s_setprio 1
	s_waitcnt lgkmcnt(0)
	v_mfma_f32_16x16x32_bf16 v[12:15], v[214:217], v[138:141], v[114:117]
	v_mfma_f32_16x16x32_bf16 v[32:35], v[222:225], v[138:141], v[32:35]
	v_mfma_f32_16x16x32_bf16 v[48:51], v[222:225], v[178:181], v[48:51]
	v_mfma_f32_16x16x32_bf16 v[52:55], v[214:217], v[190:193], v[52:55]
	v_mfma_f32_16x16x32_bf16 v[56:59], v[222:225], v[190:193], v[56:59]
	v_mfma_f32_16x16x32_bf16 v[12:15], v[218:221], v[142:145], v[12:15]
	v_mfma_f32_16x16x32_bf16 v[32:35], v[226:229], v[142:145], v[32:35]
	v_mfma_f32_16x16x32_bf16 v[36:39], v[214:217], v[170:173], v[36:39]
	v_mfma_f32_16x16x32_bf16 v[40:43], v[222:225], v[170:173], v[40:43]
	v_mfma_f32_16x16x32_bf16 v[44:47], v[214:217], v[178:181], v[44:47]
	v_mfma_f32_16x16x32_bf16 v[48:51], v[226:229], v[182:185], v[48:51]
	v_mfma_f32_16x16x32_bf16 v[52:55], v[218:221], v[194:197], v[52:55]
	v_mfma_f32_16x16x32_bf16 v[56:59], v[226:229], v[194:197], v[56:59]
	v_mfma_f32_16x16x32_bf16 v[36:39], v[218:221], v[174:177], v[36:39]
	v_mfma_f32_16x16x32_bf16 v[40:43], v[226:229], v[174:177], v[40:43]
	v_mfma_f32_16x16x32_bf16 v[44:47], v[218:221], v[182:185], v[44:47]
	s_setprio 0
	s_mov_b32 m0, s11
	v_lshl_add_u64 v[8:9], v[8:9], 0, s[40:41]
	s_barrier
	ds_read_b128 v[114:117], v252 offset:49152
	ds_read_b128 v[138:141], v252 offset:50176
	ds_read_b128 v[142:145], v252 offset:51200
	ds_read_b128 v[170:173], v252 offset:52224
	ds_read_b128 v[174:177], v252 offset:53248
	ds_read_b128 v[178:181], v252 offset:54272
	ds_read_b128 v[182:185], v252 offset:55296
	ds_read_b128 v[190:193], v252 offset:56320
	global_load_lds_dwordx4 v[8:9], off
	v_lshl_add_u64 v[8:9], v[10:11], 0, s[40:41]
	s_mov_b32 m0, s10
	s_nop 0
	global_load_lds_dwordx4 v[8:9], off
	s_waitcnt vmcnt(4)
	s_barrier
	s_waitcnt lgkmcnt(0)
	s_setprio 1
	s_waitcnt lgkmcnt(0)
	v_mfma_f32_16x16x32_bf16 v[8:11], v[106:109], v[114:117], v[146:149]
	v_mfma_f32_16x16x32_bf16 v[20:23], v[130:133], v[182:185], v[20:23]
	v_mfma_f32_16x16x32_bf16 v[8:11], v[110:113], v[138:141], v[8:11]
	v_mfma_f32_16x16x32_bf16 v[146:149], v[130:133], v[114:117], v[150:153]
	v_mfma_f32_16x16x32_bf16 v[150:153], v[106:109], v[142:145], v[154:157]
	v_mfma_f32_16x16x32_bf16 v[154:157], v[130:133], v[142:145], v[158:161]
	v_mfma_f32_16x16x32_bf16 v[158:161], v[106:109], v[174:177], v[162:165]
	v_mfma_f32_16x16x32_bf16 v[162:165], v[130:133], v[174:177], v[166:169]
	v_mfma_f32_16x16x32_bf16 v[16:19], v[106:109], v[182:185], v[16:19]
	v_mfma_f32_16x16x32_bf16 v[20:23], v[134:137], v[190:193], v[20:23]
	v_mfma_f32_16x16x32_bf16 v[146:149], v[134:137], v[138:141], v[146:149]
	v_mfma_f32_16x16x32_bf16 v[150:153], v[110:113], v[170:173], v[150:153]
	v_mfma_f32_16x16x32_bf16 v[154:157], v[134:137], v[170:173], v[154:157]
	v_mfma_f32_16x16x32_bf16 v[158:161], v[110:113], v[178:181], v[158:161]
	v_mfma_f32_16x16x32_bf16 v[162:165], v[134:137], v[178:181], v[162:165]
	v_mfma_f32_16x16x32_bf16 v[16:19], v[110:113], v[190:193], v[16:19]
	s_setprio 0
	s_mov_b32 m0, s3
	v_lshl_add_u64 v[4:5], v[4:5], 0, s[40:41]
	global_load_lds_dwordx4 v[4:5], off
	v_lshl_add_u64 v[4:5], v[6:7], 0, s[40:41]
	s_mov_b32 m0, s1
	s_nop 0
	global_load_lds_dwordx4 v[4:5], off
	s_waitcnt vmcnt(6)
	s_setprio 1
	v_mfma_f32_16x16x32_bf16 v[4:7], v[214:217], v[114:117], v[24:27]
	v_mfma_f32_16x16x32_bf16 v[24:27], v[222:225], v[114:117], v[28:31]
	v_mfma_f32_16x16x32_bf16 v[28:31], v[214:217], v[142:145], v[60:63]
	v_mfma_f32_16x16x32_bf16 v[60:63], v[222:225], v[142:145], v[118:121]
	v_mfma_f32_16x16x32_bf16 v[106:109], v[214:217], v[174:177], v[122:125]
	v_mfma_f32_16x16x32_bf16 v[110:113], v[222:225], v[174:177], v[126:129]
	v_mfma_f32_16x16x32_bf16 v[98:101], v[214:217], v[182:185], v[98:101]
	v_mfma_f32_16x16x32_bf16 v[102:105], v[222:225], v[182:185], v[102:105]
	v_mfma_f32_16x16x32_bf16 v[4:7], v[218:221], v[138:141], v[4:7]
	v_mfma_f32_16x16x32_bf16 v[24:27], v[226:229], v[138:141], v[24:27]
	v_mfma_f32_16x16x32_bf16 v[28:31], v[218:221], v[170:173], v[28:31]
	v_mfma_f32_16x16x32_bf16 v[60:63], v[226:229], v[170:173], v[60:63]
	v_mfma_f32_16x16x32_bf16 v[106:109], v[218:221], v[178:181], v[106:109]
	v_mfma_f32_16x16x32_bf16 v[110:113], v[226:229], v[178:181], v[110:113]
	v_mfma_f32_16x16x32_bf16 v[98:101], v[218:221], v[190:193], v[98:101]
	v_mfma_f32_16x16x32_bf16 v[102:105], v[226:229], v[190:193], v[102:105]
	s_setprio 0
	s_mov_b32 m0, s7
	v_lshl_add_u64 v[0:1], v[0:1], 0, s[40:41]
	s_barrier
	ds_read_b128 v[114:117], v64
	ds_read_b128 v[118:121], v64 offset:1024
	ds_read_b128 v[122:125], v64 offset:2048
	ds_read_b128 v[126:129], v64 offset:3072
	ds_read_b128 v[130:133], v252
	ds_read_b128 v[134:137], v252 offset:1024
	ds_read_b128 v[138:141], v252 offset:2048
	ds_read_b128 v[142:145], v252 offset:3072
	ds_read_b128 v[166:169], v252 offset:4096
	ds_read_b128 v[170:173], v252 offset:5120
	ds_read_b128 v[174:177], v252 offset:6144
	ds_read_b128 v[178:181], v252 offset:7168
	global_load_lds_dwordx4 v[0:1], off
	v_lshl_add_u64 v[0:1], v[2:3], 0, s[40:41]
	s_mov_b32 m0, s6
	s_nop 0
	global_load_lds_dwordx4 v[0:1], off
	s_barrier
	s_waitcnt lgkmcnt(0)
	s_setprio 1
	s_waitcnt lgkmcnt(0)
	v_mfma_f32_16x16x32_bf16 v[0:3], v[114:117], v[130:133], v[66:69]
	v_mfma_f32_16x16x32_bf16 v[66:69], v[122:125], v[130:133], v[70:73]
	v_mfma_f32_16x16x32_bf16 v[70:73], v[114:117], v[138:141], v[74:77]
	v_mfma_f32_16x16x32_bf16 v[74:77], v[122:125], v[138:141], v[78:81]
	v_mfma_f32_16x16x32_bf16 v[78:81], v[114:117], v[166:169], v[82:85]
	v_mfma_f32_16x16x32_bf16 v[82:85], v[122:125], v[166:169], v[86:89]
	v_mfma_f32_16x16x32_bf16 v[86:89], v[114:117], v[174:177], v[90:93]
	v_mfma_f32_16x16x32_bf16 v[90:93], v[122:125], v[174:177], v[94:97]
	v_mfma_f32_16x16x32_bf16 v[0:3], v[118:121], v[134:137], v[0:3]
	v_mfma_f32_16x16x32_bf16 v[66:69], v[126:129], v[134:137], v[66:69]
	v_mfma_f32_16x16x32_bf16 v[70:73], v[118:121], v[142:145], v[70:73]
	v_mfma_f32_16x16x32_bf16 v[74:77], v[126:129], v[142:145], v[74:77]
	v_mfma_f32_16x16x32_bf16 v[78:81], v[118:121], v[170:173], v[78:81]
	v_mfma_f32_16x16x32_bf16 v[82:85], v[126:129], v[170:173], v[82:85]
	v_mfma_f32_16x16x32_bf16 v[86:89], v[118:121], v[178:181], v[86:89]
	v_mfma_f32_16x16x32_bf16 v[90:93], v[126:129], v[178:181], v[90:93]
	s_setprio 0
	s_barrier
	ds_read_b128 v[94:97], v198
	ds_read_b128 v[182:185], v198 offset:1024
	ds_read_b128 v[190:193], v198 offset:2048
	ds_read_b128 v[194:197], v198 offset:3072
	s_barrier
	s_waitcnt lgkmcnt(0)
	s_setprio 1
	s_waitcnt lgkmcnt(0)
	v_mfma_f32_16x16x32_bf16 v[12:15], v[94:97], v[130:133], v[12:15]
	v_mfma_f32_16x16x32_bf16 v[32:35], v[190:193], v[130:133], v[32:35]
	v_mfma_f32_16x16x32_bf16 v[48:51], v[190:193], v[166:169], v[48:51]
	v_mfma_f32_16x16x32_bf16 v[52:55], v[94:97], v[174:177], v[52:55]
	v_mfma_f32_16x16x32_bf16 v[56:59], v[190:193], v[174:177], v[56:59]
	v_mfma_f32_16x16x32_bf16 v[12:15], v[182:185], v[134:137], v[12:15]
	v_mfma_f32_16x16x32_bf16 v[32:35], v[194:197], v[134:137], v[32:35]
	v_mfma_f32_16x16x32_bf16 v[36:39], v[94:97], v[138:141], v[36:39]
	v_mfma_f32_16x16x32_bf16 v[40:43], v[190:193], v[138:141], v[40:43]
	v_mfma_f32_16x16x32_bf16 v[44:47], v[94:97], v[166:169], v[44:47]
	v_mfma_f32_16x16x32_bf16 v[48:51], v[194:197], v[170:173], v[48:51]
	v_mfma_f32_16x16x32_bf16 v[52:55], v[182:185], v[178:181], v[52:55]
	v_mfma_f32_16x16x32_bf16 v[56:59], v[194:197], v[178:181], v[56:59]
	v_mfma_f32_16x16x32_bf16 v[36:39], v[182:185], v[142:145], v[36:39]
	v_mfma_f32_16x16x32_bf16 v[40:43], v[194:197], v[142:145], v[40:43]
	v_mfma_f32_16x16x32_bf16 v[44:47], v[182:185], v[170:173], v[44:47]
	s_setprio 0
	s_barrier
	ds_read_b128 v[130:133], v252 offset:16384
	ds_read_b128 v[134:137], v252 offset:17408
	ds_read_b128 v[138:141], v252 offset:18432
	ds_read_b128 v[142:145], v252 offset:19456
	ds_read_b128 v[166:169], v252 offset:20480
	ds_read_b128 v[170:173], v252 offset:21504
	ds_read_b128 v[174:177], v252 offset:22528
	ds_read_b128 v[178:181], v252 offset:23552
	s_waitcnt vmcnt(4)
	s_barrier
	s_waitcnt lgkmcnt(0)
	s_setprio 1
	s_waitcnt lgkmcnt(0)
	v_mfma_f32_16x16x32_bf16 v[8:11], v[114:117], v[130:133], v[8:11]
	v_mfma_f32_16x16x32_bf16 v[20:23], v[122:125], v[174:177], v[20:23]
	v_mfma_f32_16x16x32_bf16 v[8:11], v[118:121], v[134:137], v[8:11]
	v_mfma_f32_16x16x32_bf16 v[146:149], v[122:125], v[130:133], v[146:149]
	v_mfma_f32_16x16x32_bf16 v[150:153], v[114:117], v[138:141], v[150:153]
	v_mfma_f32_16x16x32_bf16 v[154:157], v[122:125], v[138:141], v[154:157]
	v_mfma_f32_16x16x32_bf16 v[158:161], v[114:117], v[166:169], v[158:161]
	v_mfma_f32_16x16x32_bf16 v[162:165], v[122:125], v[166:169], v[162:165]
	v_mfma_f32_16x16x32_bf16 v[16:19], v[114:117], v[174:177], v[16:19]
	v_mfma_f32_16x16x32_bf16 v[20:23], v[126:129], v[178:181], v[20:23]
	v_mfma_f32_16x16x32_bf16 v[146:149], v[126:129], v[134:137], v[146:149]
	v_mfma_f32_16x16x32_bf16 v[150:153], v[118:121], v[142:145], v[150:153]
	v_mfma_f32_16x16x32_bf16 v[154:157], v[126:129], v[142:145], v[154:157]
	v_mfma_f32_16x16x32_bf16 v[158:161], v[118:121], v[170:173], v[158:161]
	v_mfma_f32_16x16x32_bf16 v[162:165], v[126:129], v[170:173], v[162:165]
	v_mfma_f32_16x16x32_bf16 v[16:19], v[118:121], v[178:181], v[16:19]
	s_setprio 0
	s_setprio 1
	v_mfma_f32_16x16x32_bf16 v[4:7], v[94:97], v[130:133], v[4:7]
	v_mfma_f32_16x16x32_bf16 v[214:217], v[182:185], v[134:137], v[4:7]
	v_mfma_f32_16x16x32_bf16 v[4:7], v[190:193], v[130:133], v[24:27]
	v_mfma_f32_16x16x32_bf16 v[218:221], v[194:197], v[134:137], v[4:7]
	v_mfma_f32_16x16x32_bf16 v[4:7], v[94:97], v[138:141], v[28:31]
	v_mfma_f32_16x16x32_bf16 v[28:31], v[182:185], v[142:145], v[4:7]
	v_mfma_f32_16x16x32_bf16 v[4:7], v[190:193], v[138:141], v[60:63]
	v_mfma_f32_16x16x32_bf16 v[222:225], v[194:197], v[142:145], v[4:7]
	v_mfma_f32_16x16x32_bf16 v[4:7], v[94:97], v[166:169], v[106:109]
	v_mfma_f32_16x16x32_bf16 v[226:229], v[182:185], v[170:173], v[4:7]
	v_mfma_f32_16x16x32_bf16 v[4:7], v[190:193], v[166:169], v[110:113]
	v_mfma_f32_16x16x32_bf16 v[166:169], v[194:197], v[170:173], v[4:7]
	v_mfma_f32_16x16x32_bf16 v[4:7], v[94:97], v[174:177], v[98:101]
	v_mfma_f32_16x16x32_bf16 v[170:173], v[182:185], v[178:181], v[4:7]
	v_mfma_f32_16x16x32_bf16 v[4:7], v[190:193], v[174:177], v[102:105]
	v_mfma_f32_16x16x32_bf16 v[174:177], v[194:197], v[178:181], v[4:7]
	s_setprio 0
	s_barrier
	s_nop 4
	ds_read_b128 v[4:7], v199
	ds_read_b128 v[178:181], v199 offset:1024
	ds_read_b128 v[182:185], v199 offset:2048
	ds_read_b128 v[190:193], v199 offset:3072
	ds_read_b128 v[24:27], v252 offset:32768
	ds_read_b128 v[60:63], v252 offset:33792
	ds_read_b128 v[106:109], v252 offset:34816
	ds_read_b128 v[110:113], v252 offset:35840
	ds_read_b128 v[194:197], v252 offset:36864
	ds_read_b128 v[230:233], v252 offset:37888
	ds_read_b128 v[234:237], v252 offset:38912
	ds_read_b128 v[238:241], v252 offset:39936
	s_waitcnt vmcnt(2)
	s_barrier
	s_waitcnt lgkmcnt(0)
	s_setprio 1
	s_waitcnt lgkmcnt(0)
	v_mfma_f32_16x16x32_bf16 v[0:3], v[4:7], v[24:27], v[0:3]
	v_mfma_f32_16x16x32_bf16 v[130:133], v[178:181], v[60:63], v[0:3]
	v_mfma_f32_16x16x32_bf16 v[0:3], v[182:185], v[24:27], v[66:69]
	v_mfma_f32_16x16x32_bf16 v[134:137], v[190:193], v[60:63], v[0:3]
	v_mfma_f32_16x16x32_bf16 v[0:3], v[4:7], v[106:109], v[70:73]
	v_mfma_f32_16x16x32_bf16 v[114:117], v[178:181], v[110:113], v[0:3]
	v_mfma_f32_16x16x32_bf16 v[0:3], v[182:185], v[106:109], v[74:77]
	v_mfma_f32_16x16x32_bf16 v[118:121], v[190:193], v[110:113], v[0:3]
	v_mfma_f32_16x16x32_bf16 v[0:3], v[4:7], v[194:197], v[78:81]
	v_mfma_f32_16x16x32_bf16 v[98:101], v[178:181], v[230:233], v[0:3]
	v_mfma_f32_16x16x32_bf16 v[0:3], v[182:185], v[194:197], v[82:85]
	v_mfma_f32_16x16x32_bf16 v[102:105], v[190:193], v[230:233], v[0:3]
	v_mfma_f32_16x16x32_bf16 v[0:3], v[4:7], v[234:237], v[86:89]
	v_mfma_f32_16x16x32_bf16 v[94:97], v[178:181], v[238:241], v[0:3]
	v_mfma_f32_16x16x32_bf16 v[0:3], v[182:185], v[234:237], v[90:93]
	v_mfma_f32_16x16x32_bf16 v[90:93], v[190:193], v[238:241], v[0:3]
	s_setprio 0
	s_barrier
	s_nop 4
	ds_read_b128 v[0:3], v200
	ds_read_b128 v[242:245], v200 offset:1024
	ds_read_b128 v[246:249], v200 offset:2048
	ds_read_b128 v[198:201], v200 offset:3072
	s_waitcnt vmcnt(0)
	s_barrier
	s_waitcnt lgkmcnt(0)
	s_setprio 1
	s_waitcnt lgkmcnt(0)
	v_mfma_f32_16x16x32_bf16 v[12:15], v[0:3], v[24:27], v[12:15]
	v_mfma_f32_16x16x32_bf16 v[138:141], v[242:245], v[60:63], v[12:15]
	v_mfma_f32_16x16x32_bf16 v[12:15], v[246:249], v[24:27], v[32:35]
	v_mfma_f32_16x16x32_bf16 v[142:145], v[198:201], v[60:63], v[12:15]
	v_mfma_f32_16x16x32_bf16 v[12:15], v[0:3], v[106:109], v[36:39]
	v_mfma_f32_16x16x32_bf16 v[122:125], v[242:245], v[110:113], v[12:15]
	v_mfma_f32_16x16x32_bf16 v[12:15], v[246:249], v[106:109], v[40:43]
	v_mfma_f32_16x16x32_bf16 v[126:129], v[198:201], v[110:113], v[12:15]
	v_mfma_f32_16x16x32_bf16 v[12:15], v[0:3], v[194:197], v[44:47]
	v_mfma_f32_16x16x32_bf16 v[106:109], v[242:245], v[230:233], v[12:15]
	v_mfma_f32_16x16x32_bf16 v[12:15], v[246:249], v[194:197], v[48:51]
	v_mfma_f32_16x16x32_bf16 v[110:113], v[198:201], v[230:233], v[12:15]
	v_mfma_f32_16x16x32_bf16 v[12:15], v[0:3], v[234:237], v[52:55]
	v_mfma_f32_16x16x32_bf16 v[86:89], v[242:245], v[238:241], v[12:15]
	v_mfma_f32_16x16x32_bf16 v[12:15], v[246:249], v[234:237], v[56:59]
	v_mfma_f32_16x16x32_bf16 v[82:85], v[198:201], v[238:241], v[12:15]
	s_setprio 0
	s_barrier
	ds_read_b128 v[36:39], v252 offset:49152
	ds_read_b128 v[40:43], v252 offset:50176
	ds_read_b128 v[44:47], v252 offset:51200
	ds_read_b128 v[48:51], v252 offset:52224
	ds_read_b128 v[194:197], v252 offset:53248
	ds_read_b128 v[230:233], v252 offset:54272
	ds_read_b128 v[234:237], v252 offset:55296
	ds_read_b128 v[238:241], v252 offset:56320
	s_barrier
	s_waitcnt lgkmcnt(0)
	s_setprio 1
	s_waitcnt lgkmcnt(0)
	v_mfma_f32_16x16x32_bf16 v[8:11], v[4:7], v[36:39], v[8:11]
	v_mfma_f32_16x16x32_bf16 v[78:81], v[178:181], v[40:43], v[8:11]
	v_mfma_f32_16x16x32_bf16 v[8:11], v[182:185], v[36:39], v[146:149]
	v_mfma_f32_16x16x32_bf16 v[70:73], v[190:193], v[40:43], v[8:11]
	v_mfma_f32_16x16x32_bf16 v[8:11], v[4:7], v[44:47], v[150:153]
	v_mfma_f32_16x16x32_bf16 v[60:63], v[178:181], v[48:51], v[8:11]
	v_mfma_f32_16x16x32_bf16 v[8:11], v[182:185], v[44:47], v[154:157]
	v_mfma_f32_16x16x32_bf16 v[52:55], v[190:193], v[48:51], v[8:11]
	v_mfma_f32_16x16x32_bf16 v[8:11], v[4:7], v[194:197], v[158:161]
	v_mfma_f32_16x16x32_bf16 v[4:7], v[4:7], v[234:237], v[16:19]
	v_mfma_f32_16x16x32_bf16 v[32:35], v[178:181], v[230:233], v[8:11]
	v_mfma_f32_16x16x32_bf16 v[8:11], v[182:185], v[194:197], v[162:165]
	v_mfma_f32_16x16x32_bf16 v[12:15], v[178:181], v[238:241], v[4:7]
	v_mfma_f32_16x16x32_bf16 v[4:7], v[182:185], v[234:237], v[20:23]
	v_mfma_f32_16x16x32_bf16 v[24:27], v[190:193], v[230:233], v[8:11]
	v_mfma_f32_16x16x32_bf16 v[4:7], v[190:193], v[238:241], v[4:7]
	s_setprio 0
	s_setprio 1
	v_mfma_f32_16x16x32_bf16 v[8:11], v[0:3], v[36:39], v[214:217]
	v_mfma_f32_16x16x32_bf16 v[74:77], v[242:245], v[40:43], v[8:11]
	v_mfma_f32_16x16x32_bf16 v[8:11], v[246:249], v[36:39], v[218:221]
	v_mfma_f32_16x16x32_bf16 v[66:69], v[198:201], v[40:43], v[8:11]
	v_mfma_f32_16x16x32_bf16 v[8:11], v[0:3], v[44:47], v[28:31]
	v_mfma_f32_16x16x32_bf16 v[56:59], v[242:245], v[48:51], v[8:11]
	v_mfma_f32_16x16x32_bf16 v[8:11], v[246:249], v[44:47], v[222:225]
	v_mfma_f32_16x16x32_bf16 v[48:51], v[198:201], v[48:51], v[8:11]
	v_mfma_f32_16x16x32_bf16 v[8:11], v[0:3], v[194:197], v[226:229]
	v_mfma_f32_16x16x32_bf16 v[28:31], v[242:245], v[230:233], v[8:11]
	v_mfma_f32_16x16x32_bf16 v[8:11], v[246:249], v[194:197], v[166:169]
	v_mfma_f32_16x16x32_bf16 v[0:3], v[0:3], v[234:237], v[170:173]
	v_mfma_f32_16x16x32_bf16 v[20:23], v[198:201], v[230:233], v[8:11]
	v_mfma_f32_16x16x32_bf16 v[8:11], v[242:245], v[238:241], v[0:3]
	v_mfma_f32_16x16x32_bf16 v[0:3], v[246:249], v[234:237], v[174:177]
	v_mfma_f32_16x16x32_bf16 v[0:3], v[198:201], v[238:241], v[0:3]
	s_setprio 0
	v_readlane_b32 s6, v255, 21
	v_readlane_b32 s7, v255, 22
	s_andn2_b64 vcc, exec, s[6:7]
	s_barrier
	s_cbranch_vccnz .LBB0_276
	s_barrier
